# P10 and P6 row loops: loop-invariant gain chunks and the row's shift/scale chunks loaded up front instead of per chunk behind vmcnt(0) waits
# baseline (speedup 1.0000x reference)
.LBB0_837:
	s_cmp_gt_i32 s54, 15
	s_cselect_b32 s2, 1, 0
	s_lshl_b32 s54, s54, 8
	s_add_i32 s54, s54, s44
	s_lshl_b32 s6, s55, 8
	s_or_b32 s60, s6, s45
	v_or_b32_e32 v216, s54, v200
	v_mul_u32_u24_e32 v217, 0x90, v216
	v_add_u32_e32 v218, 0x1200, v217
	global_load_dwordx4 v[112:115], v217, s[12:13]
	global_load_dwordx4 v[116:119], v217, s[12:13] offset:16
	global_load_dwordx4 v[120:123], v217, s[12:13] offset:32
	global_load_dwordx4 v[132:135], v217, s[12:13] offset:2304
	global_load_dwordx4 v[136:139], v217, s[12:13] offset:2320
	global_load_dwordx4 v[140:143], v217, s[12:13] offset:2336
	global_load_dwordx4 v[152:155], v218, s[12:13]
	global_load_dwordx4 v[156:159], v218, s[12:13] offset:16
	global_load_dwordx4 v[160:163], v218, s[12:13] offset:32
	global_load_dwordx4 v[184:187], v218, s[12:13] offset:2304
	global_load_dwordx4 v[188:191], v218, s[12:13] offset:2320
	global_load_dwordx4 v[192:195], v218, s[12:13] offset:2336
	s_mul_hi_i32 s6, s60, 0x2aaaaaab
	s_lshr_b32 s7, s6, 31
	s_lshr_b32 s6, s6, 4
	s_add_i32 s6, s6, s7
	s_mulk_i32 s6, 0x60
	s_sub_i32 s6, s60, s6
	s_cmp_eq_u32 s6, 64
	s_cselect_b32 s61, 1, 0
	s_and_b32 s61, s61, s2
	s_or_b32 s8, s60, 0x80
	s_mul_hi_i32 s6, s8, 0x2aaaaaab
	s_lshr_b32 s7, s6, 31
	s_lshr_b32 s6, s6, 4
	s_add_i32 s6, s6, s7
	s_mulk_i32 s6, 0x60
	s_sub_i32 s6, s8, s6
	s_cmp_eq_u32 s6, 64
	s_cselect_b32 s62, 1, 0
	s_and_b32 s62, s62, s2
	s_bfe_u32 s55, s54, 0x40006
	v_xor_b32_e32 v213, 16, v209
	v_lshlrev_b32_e32 v213, 2, v213
	v_mul_u32_u24_e32 v211, 0x600, v216
	s_lshl_b32 s6, s60, 1
	v_add3_u32 v211, v211, v172, s6
	v_add_u32_e32 v217, 0x4800, v217
	v_add_u32_e32 v218, 0x4800, v218
	s_waitcnt vmcnt(0)
	v_pk_add_f32 v[112:113], v[112:113], v[114:115]
	v_pk_add_f32 v[116:117], v[116:117], v[118:119]
	v_pk_add_f32 v[120:121], v[120:121], v[122:123]
	v_pk_add_f32 v[112:113], v[112:113], v[116:117]
	v_pk_add_f32 v[112:113], v[112:113], v[120:121]
	v_add_f32_e32 v112, v112, v113
	v_fmamk_f32 v112, v112, 0x3b2aaaab, v208
	v_pk_add_f32 v[132:133], v[132:133], v[134:135]
	v_pk_add_f32 v[136:137], v[136:137], v[138:139]
	v_pk_add_f32 v[140:141], v[140:141], v[142:143]
	v_pk_add_f32 v[132:133], v[132:133], v[136:137]
	v_pk_add_f32 v[132:133], v[132:133], v[140:141]
	v_add_f32_e32 v132, v132, v133
	v_fmamk_f32 v132, v132, 0x3b2aaaab, v208
	v_pk_add_f32 v[152:153], v[152:153], v[154:155]
	v_pk_add_f32 v[156:157], v[156:157], v[158:159]
	v_pk_add_f32 v[160:161], v[160:161], v[162:163]
	v_pk_add_f32 v[152:153], v[152:153], v[156:157]
	v_pk_add_f32 v[152:153], v[152:153], v[160:161]
	v_add_f32_e32 v152, v152, v153
	v_fmamk_f32 v152, v152, 0x3b2aaaab, v208
	v_pk_add_f32 v[184:185], v[184:185], v[186:187]
	v_pk_add_f32 v[188:189], v[188:189], v[190:191]
	v_pk_add_f32 v[192:193], v[192:193], v[194:195]
	v_pk_add_f32 v[184:185], v[184:185], v[188:189]
	v_pk_add_f32 v[184:185], v[184:185], v[192:193]
	v_add_f32_e32 v184, v184, v185
	v_fmamk_f32 v184, v184, 0x3b2aaaab, v208
	v_rsq_f32_e32 v196, v112
	v_rsq_f32_e32 v198, v132
	v_rsq_f32_e32 v210, v152
	v_rsq_f32_e32 v212, v184
	s_nop 0
	v_mul_f32_e32 v196, 0x3e16c740, v196
	v_mul_f32_e32 v198, 0x3e16c740, v198
	v_mul_f32_e32 v210, 0x3e16c740, v210
	v_mul_f32_e32 v212, 0x3e16c740, v212
	global_load_dwordx4 v[112:115], v217, s[12:13]
	global_load_dwordx4 v[116:119], v217, s[12:13] offset:16
	global_load_dwordx4 v[120:123], v217, s[12:13] offset:32
	global_load_dwordx4 v[132:135], v217, s[12:13] offset:2304
	global_load_dwordx4 v[136:139], v217, s[12:13] offset:2320
	global_load_dwordx4 v[140:143], v217, s[12:13] offset:2336
	global_load_dwordx4 v[152:155], v218, s[12:13]
	global_load_dwordx4 v[156:159], v218, s[12:13] offset:16
	global_load_dwordx4 v[160:163], v218, s[12:13] offset:32
	global_load_dwordx4 v[184:187], v218, s[12:13] offset:2304
	global_load_dwordx4 v[188:191], v218, s[12:13] offset:2320
	global_load_dwordx4 v[192:195], v218, s[12:13] offset:2336
	s_add_i32 s6, s54, 0x80
	s_bfe_u32 s7, s6, 0x40006
	s_cmp_lg_u32 s61, 0
	s_cbranch_scc1 .Lq2_v0
	s_cmp_lg_u32 s62, 0
	s_cbranch_scc1 .Lq2_v1
	v_pk_mul_f32 v[148:149], v[148:149], v[196:197] op_sel_hi:[1,0]
	v_pk_mul_f32 v[150:151], v[150:151], v[196:197] op_sel_hi:[1,0]
	v_pk_mul_f32 v[144:145], v[144:145], v[196:197] op_sel_hi:[1,0]
	v_pk_mul_f32 v[146:147], v[146:147], v[196:197] op_sel_hi:[1,0]
	v_cvt_pk_bf16_f32 v148, v148, v149
	v_cvt_pk_bf16_f32 v149, v150, v151
	v_cvt_pk_bf16_f32 v150, v144, v145
	v_cvt_pk_bf16_f32 v151, v146, v147
	global_store_dwordx4 v211, v[148:151], s[16:17]
	v_pk_mul_f32 v[128:129], v[128:129], v[196:197] op_sel_hi:[1,0]
	v_pk_mul_f32 v[130:131], v[130:131], v[196:197] op_sel_hi:[1,0]
	v_pk_mul_f32 v[124:125], v[124:125], v[196:197] op_sel_hi:[1,0]
	v_pk_mul_f32 v[126:127], v[126:127], v[196:197] op_sel_hi:[1,0]
	v_cvt_pk_bf16_f32 v128, v128, v129
	v_cvt_pk_bf16_f32 v129, v130, v131
	v_cvt_pk_bf16_f32 v130, v124, v125
	v_cvt_pk_bf16_f32 v131, v126, v127
	global_store_dwordx4 v211, v[128:131], s[16:17] offset:256
	v_add_u32_e32 v144, 0x6000, v211
	v_pk_mul_f32 v[108:109], v[108:109], v[198:199] op_sel_hi:[1,0]
	v_pk_mul_f32 v[110:111], v[110:111], v[198:199] op_sel_hi:[1,0]
	v_pk_mul_f32 v[104:105], v[104:105], v[198:199] op_sel_hi:[1,0]
	v_pk_mul_f32 v[106:107], v[106:107], v[198:199] op_sel_hi:[1,0]
	v_cvt_pk_bf16_f32 v108, v108, v109
	v_cvt_pk_bf16_f32 v109, v110, v111
	v_cvt_pk_bf16_f32 v110, v104, v105
	v_cvt_pk_bf16_f32 v111, v106, v107
	global_store_dwordx4 v144, v[108:111], s[16:17]
	v_pk_mul_f32 v[100:101], v[100:101], v[198:199] op_sel_hi:[1,0]
	v_pk_mul_f32 v[102:103], v[102:103], v[198:199] op_sel_hi:[1,0]
	v_pk_mul_f32 v[96:97], v[96:97], v[198:199] op_sel_hi:[1,0]
	v_pk_mul_f32 v[98:99], v[98:99], v[198:199] op_sel_hi:[1,0]
	v_cvt_pk_bf16_f32 v100, v100, v101
	v_cvt_pk_bf16_f32 v101, v102, v103
	v_cvt_pk_bf16_f32 v102, v96, v97
	v_cvt_pk_bf16_f32 v103, v98, v99
	global_store_dwordx4 v144, v[100:103], s[16:17] offset:256
	v_add_u32_e32 v104, 0xc000, v211
	v_pk_mul_f32 v[92:93], v[92:93], v[210:211] op_sel_hi:[1,0]
	v_pk_mul_f32 v[94:95], v[94:95], v[210:211] op_sel_hi:[1,0]
	v_pk_mul_f32 v[88:89], v[88:89], v[210:211] op_sel_hi:[1,0]
	v_pk_mul_f32 v[90:91], v[90:91], v[210:211] op_sel_hi:[1,0]
	v_cvt_pk_bf16_f32 v92, v92, v93
	v_cvt_pk_bf16_f32 v93, v94, v95
	v_cvt_pk_bf16_f32 v94, v88, v89
	v_cvt_pk_bf16_f32 v95, v90, v91
	global_store_dwordx4 v104, v[92:95], s[16:17]
	v_pk_mul_f32 v[84:85], v[84:85], v[210:211] op_sel_hi:[1,0]
	v_pk_mul_f32 v[86:87], v[86:87], v[210:211] op_sel_hi:[1,0]
	v_pk_mul_f32 v[80:81], v[80:81], v[210:211] op_sel_hi:[1,0]
	v_pk_mul_f32 v[82:83], v[82:83], v[210:211] op_sel_hi:[1,0]
	v_cvt_pk_bf16_f32 v84, v84, v85
	v_cvt_pk_bf16_f32 v85, v86, v87
	v_cvt_pk_bf16_f32 v86, v80, v81
	v_cvt_pk_bf16_f32 v87, v82, v83
	global_store_dwordx4 v104, v[84:87], s[16:17] offset:256
	v_add_u32_e32 v88, 0x12000, v211
	v_pk_mul_f32 v[76:77], v[76:77], v[212:213] op_sel_hi:[1,0]
	v_pk_mul_f32 v[78:79], v[78:79], v[212:213] op_sel_hi:[1,0]
	v_pk_mul_f32 v[72:73], v[72:73], v[212:213] op_sel_hi:[1,0]
	v_pk_mul_f32 v[74:75], v[74:75], v[212:213] op_sel_hi:[1,0]
	v_cvt_pk_bf16_f32 v76, v76, v77
	v_cvt_pk_bf16_f32 v77, v78, v79
	v_cvt_pk_bf16_f32 v78, v72, v73
	v_cvt_pk_bf16_f32 v79, v74, v75
	global_store_dwordx4 v88, v[76:79], s[16:17]
	v_pk_mul_f32 v[68:69], v[68:69], v[212:213] op_sel_hi:[1,0]
	v_pk_mul_f32 v[70:71], v[70:71], v[212:213] op_sel_hi:[1,0]
	v_pk_mul_f32 v[64:65], v[64:65], v[212:213] op_sel_hi:[1,0]
	v_pk_mul_f32 v[66:67], v[66:67], v[212:213] op_sel_hi:[1,0]
	v_cvt_pk_bf16_f32 v68, v68, v69
	v_cvt_pk_bf16_f32 v69, v70, v71
	v_cvt_pk_bf16_f32 v70, v64, v65
	v_cvt_pk_bf16_f32 v71, v66, v67
	global_store_dwordx4 v88, v[68:71], s[16:17] offset:256
	s_waitcnt vmcnt(8)
	v_pk_add_f32 v[112:113], v[112:113], v[114:115]
	v_pk_add_f32 v[116:117], v[116:117], v[118:119]
	v_pk_add_f32 v[120:121], v[120:121], v[122:123]
	v_pk_add_f32 v[112:113], v[112:113], v[116:117]
	v_pk_add_f32 v[112:113], v[112:113], v[120:121]
	v_add_f32_e32 v112, v112, v113
	v_fmamk_f32 v112, v112, 0x3b2aaaab, v208
	v_pk_add_f32 v[132:133], v[132:133], v[134:135]
	v_pk_add_f32 v[136:137], v[136:137], v[138:139]
	v_pk_add_f32 v[140:141], v[140:141], v[142:143]
	v_pk_add_f32 v[132:133], v[132:133], v[136:137]
	v_pk_add_f32 v[132:133], v[132:133], v[140:141]
	v_add_f32_e32 v132, v132, v133
	v_fmamk_f32 v132, v132, 0x3b2aaaab, v208
	v_pk_add_f32 v[152:153], v[152:153], v[154:155]
	v_pk_add_f32 v[156:157], v[156:157], v[158:159]
	v_pk_add_f32 v[160:161], v[160:161], v[162:163]
	v_pk_add_f32 v[152:153], v[152:153], v[156:157]
	v_pk_add_f32 v[152:153], v[152:153], v[160:161]
	v_add_f32_e32 v152, v152, v153
	v_fmamk_f32 v152, v152, 0x3b2aaaab, v208
	v_pk_add_f32 v[184:185], v[184:185], v[186:187]
	v_pk_add_f32 v[188:189], v[188:189], v[190:191]
	v_pk_add_f32 v[192:193], v[192:193], v[194:195]
	v_pk_add_f32 v[184:185], v[184:185], v[188:189]
	v_pk_add_f32 v[184:185], v[184:185], v[192:193]
	v_add_f32_e32 v184, v184, v185
	v_fmamk_f32 v184, v184, 0x3b2aaaab, v208
	v_rsq_f32_e32 v196, v112
	v_rsq_f32_e32 v198, v132
	v_rsq_f32_e32 v210, v152
	v_rsq_f32_e32 v212, v184
	s_nop 0
	v_mul_f32_e32 v196, 0x3e16c740, v196
	v_mul_f32_e32 v198, 0x3e16c740, v198
	v_mul_f32_e32 v210, 0x3e16c740, v210
	v_mul_f32_e32 v212, 0x3e16c740, v212
	v_add_u32_e32 v72, 0x30000, v211
	v_pk_mul_f32 v[60:61], v[60:61], v[196:197] op_sel_hi:[1,0]
	v_pk_mul_f32 v[62:63], v[62:63], v[196:197] op_sel_hi:[1,0]
	v_pk_mul_f32 v[56:57], v[56:57], v[196:197] op_sel_hi:[1,0]
	v_pk_mul_f32 v[58:59], v[58:59], v[196:197] op_sel_hi:[1,0]
	v_cvt_pk_bf16_f32 v60, v60, v61
	v_cvt_pk_bf16_f32 v61, v62, v63
	v_cvt_pk_bf16_f32 v62, v56, v57
	v_cvt_pk_bf16_f32 v63, v58, v59
	global_store_dwordx4 v72, v[60:63], s[16:17]
	v_pk_mul_f32 v[52:53], v[52:53], v[196:197] op_sel_hi:[1,0]
	v_pk_mul_f32 v[54:55], v[54:55], v[196:197] op_sel_hi:[1,0]
	v_pk_mul_f32 v[48:49], v[48:49], v[196:197] op_sel_hi:[1,0]
	v_pk_mul_f32 v[50:51], v[50:51], v[196:197] op_sel_hi:[1,0]
	v_cvt_pk_bf16_f32 v52, v52, v53
	v_cvt_pk_bf16_f32 v53, v54, v55
	v_cvt_pk_bf16_f32 v54, v48, v49
	v_cvt_pk_bf16_f32 v55, v50, v51
	global_store_dwordx4 v72, v[52:55], s[16:17] offset:256
	v_add_u32_e32 v56, 0x36000, v211
	v_pk_mul_f32 v[44:45], v[44:45], v[198:199] op_sel_hi:[1,0]
	v_pk_mul_f32 v[46:47], v[46:47], v[198:199] op_sel_hi:[1,0]
	v_pk_mul_f32 v[40:41], v[40:41], v[198:199] op_sel_hi:[1,0]
	v_pk_mul_f32 v[42:43], v[42:43], v[198:199] op_sel_hi:[1,0]
	v_cvt_pk_bf16_f32 v44, v44, v45
	v_cvt_pk_bf16_f32 v45, v46, v47
	v_cvt_pk_bf16_f32 v46, v40, v41
	v_cvt_pk_bf16_f32 v47, v42, v43
	global_store_dwordx4 v56, v[44:47], s[16:17]
	v_pk_mul_f32 v[36:37], v[36:37], v[198:199] op_sel_hi:[1,0]
	v_pk_mul_f32 v[38:39], v[38:39], v[198:199] op_sel_hi:[1,0]
	v_pk_mul_f32 v[32:33], v[32:33], v[198:199] op_sel_hi:[1,0]
	v_pk_mul_f32 v[34:35], v[34:35], v[198:199] op_sel_hi:[1,0]
	v_cvt_pk_bf16_f32 v36, v36, v37
	v_cvt_pk_bf16_f32 v37, v38, v39
	v_cvt_pk_bf16_f32 v38, v32, v33
	v_cvt_pk_bf16_f32 v39, v34, v35
	global_store_dwordx4 v56, v[36:39], s[16:17] offset:256
	v_add_u32_e32 v40, 0x3c000, v211
	v_pk_mul_f32 v[28:29], v[28:29], v[210:211] op_sel_hi:[1,0]
	v_pk_mul_f32 v[30:31], v[30:31], v[210:211] op_sel_hi:[1,0]
	v_pk_mul_f32 v[24:25], v[24:25], v[210:211] op_sel_hi:[1,0]
	v_pk_mul_f32 v[26:27], v[26:27], v[210:211] op_sel_hi:[1,0]
	v_cvt_pk_bf16_f32 v28, v28, v29
	v_cvt_pk_bf16_f32 v29, v30, v31
	v_cvt_pk_bf16_f32 v30, v24, v25
	v_cvt_pk_bf16_f32 v31, v26, v27
	global_store_dwordx4 v40, v[28:31], s[16:17]
	v_pk_mul_f32 v[20:21], v[20:21], v[210:211] op_sel_hi:[1,0]
	v_pk_mul_f32 v[22:23], v[22:23], v[210:211] op_sel_hi:[1,0]
	v_pk_mul_f32 v[16:17], v[16:17], v[210:211] op_sel_hi:[1,0]
	v_pk_mul_f32 v[18:19], v[18:19], v[210:211] op_sel_hi:[1,0]
	v_cvt_pk_bf16_f32 v20, v20, v21
	v_cvt_pk_bf16_f32 v21, v22, v23
	v_cvt_pk_bf16_f32 v22, v16, v17
	v_cvt_pk_bf16_f32 v23, v18, v19
	global_store_dwordx4 v40, v[20:23], s[16:17] offset:256
	v_add_u32_e32 v24, 0x42000, v211
	v_pk_mul_f32 v[12:13], v[12:13], v[212:213] op_sel_hi:[1,0]
	v_pk_mul_f32 v[14:15], v[14:15], v[212:213] op_sel_hi:[1,0]
	v_pk_mul_f32 v[8:9], v[8:9], v[212:213] op_sel_hi:[1,0]
	v_pk_mul_f32 v[10:11], v[10:11], v[212:213] op_sel_hi:[1,0]
	v_cvt_pk_bf16_f32 v12, v12, v13
	v_cvt_pk_bf16_f32 v13, v14, v15
	v_cvt_pk_bf16_f32 v14, v8, v9
	v_cvt_pk_bf16_f32 v15, v10, v11
	global_store_dwordx4 v24, v[12:15], s[16:17]
	v_pk_mul_f32 v[4:5], v[4:5], v[212:213] op_sel_hi:[1,0]
	v_pk_mul_f32 v[6:7], v[6:7], v[212:213] op_sel_hi:[1,0]
	v_pk_mul_f32 v[0:1], v[0:1], v[212:213] op_sel_hi:[1,0]
	v_pk_mul_f32 v[2:3], v[2:3], v[212:213] op_sel_hi:[1,0]
	v_cvt_pk_bf16_f32 v4, v4, v5
	v_cvt_pk_bf16_f32 v5, v6, v7
	v_cvt_pk_bf16_f32 v6, v0, v1
	v_cvt_pk_bf16_f32 v7, v2, v3
	global_store_dwordx4 v24, v[4:7], s[16:17] offset:256
	s_branch .Lq2_end
.Lq2_v0:
	v_pk_mul_f32 v[148:149], v[148:149], v[196:197] op_sel_hi:[1,0]
	v_pk_mul_f32 v[150:151], v[150:151], v[196:197] op_sel_hi:[1,0]
	v_pk_mul_f32 v[144:145], v[144:145], v[196:197] op_sel_hi:[1,0]
	v_pk_mul_f32 v[146:147], v[146:147], v[196:197] op_sel_hi:[1,0]
	v_mov_b32_e32 v199, s55
	v_cndmask_b32_e64 v199, v200, v199, s[10:11]
	v_cvt_f32_ubyte0_e32 v199, v199
	v_mul_f32_e32 v199, v174, v199
	ds_bpermute_b32 v216, v213, v148
	ds_bpermute_b32 v217, v213, v149
	ds_bpermute_b32 v218, v213, v150
	ds_bpermute_b32 v219, v213, v151
	v_mul_f32_e32 v220, 0x3e22f983, v199
	v_mul_f32_e32 v221, 0x3d4e2601, v199
	v_mul_f32_e32 v222, 0x3c826136, v199
	v_mul_f32_e32 v223, 0x3ba4eb34, v199
	v_cos_f32_e32 v224, v220
	v_cos_f32_e32 v225, v221
	v_cos_f32_e32 v226, v222
	v_cos_f32_e32 v227, v223
	v_sin_f32_e32 v220, v220
	v_sin_f32_e32 v221, v221
	v_sin_f32_e32 v222, v222
	v_sin_f32_e32 v223, v223
	s_waitcnt lgkmcnt(0)
	v_pk_mul_f32 v[216:217], v[216:217], v[220:221]
	v_pk_mul_f32 v[218:219], v[218:219], v[222:223]
	v_pk_fma_f32 v[148:149], v[148:149], v[224:225], v[216:217]
	v_pk_fma_f32 v[150:151], v[150:151], v[226:227], v[218:219]
	ds_bpermute_b32 v216, v213, v144
	ds_bpermute_b32 v217, v213, v145
	ds_bpermute_b32 v218, v213, v146
	ds_bpermute_b32 v219, v213, v147
	v_mul_f32_e32 v220, 0x3ad09b8a, v199
	v_mul_f32_e32 v221, 0x3a03ef5d, v199
	v_mul_f32_e32 v222, 0x3926e2d4, v199
	v_mul_f32_e32 v223, 0x38531894, v199
	v_cos_f32_e32 v224, v220
	v_cos_f32_e32 v225, v221
	v_cos_f32_e32 v226, v222
	v_cos_f32_e32 v227, v223
	v_sin_f32_e32 v220, v220
	v_sin_f32_e32 v221, v221
	v_sin_f32_e32 v222, v222
	v_sin_f32_e32 v223, v223
	s_waitcnt lgkmcnt(0)
	v_pk_mul_f32 v[216:217], v[216:217], v[220:221]
	v_pk_mul_f32 v[218:219], v[218:219], v[222:223]
	v_pk_fma_f32 v[144:145], v[144:145], v[224:225], v[216:217]
	v_pk_fma_f32 v[146:147], v[146:147], v[226:227], v[218:219]
	v_cvt_pk_bf16_f32 v148, v148, v149
	v_cvt_pk_bf16_f32 v149, v150, v151
	v_cvt_pk_bf16_f32 v150, v144, v145
	v_cvt_pk_bf16_f32 v151, v146, v147
	global_store_dwordx4 v211, v[148:151], s[16:17]
	v_pk_mul_f32 v[128:129], v[128:129], v[196:197] op_sel_hi:[1,0]
	v_pk_mul_f32 v[130:131], v[130:131], v[196:197] op_sel_hi:[1,0]
	v_pk_mul_f32 v[124:125], v[124:125], v[196:197] op_sel_hi:[1,0]
	v_pk_mul_f32 v[126:127], v[126:127], v[196:197] op_sel_hi:[1,0]
	v_cvt_pk_bf16_f32 v128, v128, v129
	v_cvt_pk_bf16_f32 v129, v130, v131
	v_cvt_pk_bf16_f32 v130, v124, v125
	v_cvt_pk_bf16_f32 v131, v126, v127
	global_store_dwordx4 v211, v[128:131], s[16:17] offset:256
	v_add_u32_e32 v144, 0x6000, v211
	v_pk_mul_f32 v[108:109], v[108:109], v[198:199] op_sel_hi:[1,0]
	v_pk_mul_f32 v[110:111], v[110:111], v[198:199] op_sel_hi:[1,0]
	v_pk_mul_f32 v[104:105], v[104:105], v[198:199] op_sel_hi:[1,0]
	v_pk_mul_f32 v[106:107], v[106:107], v[198:199] op_sel_hi:[1,0]
	v_mov_b32_e32 v199, s55
	v_cndmask_b32_e64 v199, v202, v199, s[10:11]
	v_cvt_f32_ubyte0_e32 v199, v199
	v_mul_f32_e32 v199, v174, v199
	ds_bpermute_b32 v216, v213, v108
	ds_bpermute_b32 v217, v213, v109
	ds_bpermute_b32 v218, v213, v110
	ds_bpermute_b32 v219, v213, v111
	v_mul_f32_e32 v220, 0x3e22f983, v199
	v_mul_f32_e32 v221, 0x3d4e2601, v199
	v_mul_f32_e32 v222, 0x3c826136, v199
	v_mul_f32_e32 v223, 0x3ba4eb34, v199
	v_cos_f32_e32 v224, v220
	v_cos_f32_e32 v225, v221
	v_cos_f32_e32 v226, v222
	v_cos_f32_e32 v227, v223
	v_sin_f32_e32 v220, v220
	v_sin_f32_e32 v221, v221
	v_sin_f32_e32 v222, v222
	v_sin_f32_e32 v223, v223
	s_waitcnt lgkmcnt(0)
	v_pk_mul_f32 v[216:217], v[216:217], v[220:221]
	v_pk_mul_f32 v[218:219], v[218:219], v[222:223]
	v_pk_fma_f32 v[108:109], v[108:109], v[224:225], v[216:217]
	v_pk_fma_f32 v[110:111], v[110:111], v[226:227], v[218:219]
	ds_bpermute_b32 v216, v213, v104
	ds_bpermute_b32 v217, v213, v105
	ds_bpermute_b32 v218, v213, v106
	ds_bpermute_b32 v219, v213, v107
	v_mul_f32_e32 v220, 0x3ad09b8a, v199
	v_mul_f32_e32 v221, 0x3a03ef5d, v199
	v_mul_f32_e32 v222, 0x3926e2d4, v199
	v_mul_f32_e32 v223, 0x38531894, v199
	v_cos_f32_e32 v224, v220
	v_cos_f32_e32 v225, v221
	v_cos_f32_e32 v226, v222
	v_cos_f32_e32 v227, v223
	v_sin_f32_e32 v220, v220
	v_sin_f32_e32 v221, v221
	v_sin_f32_e32 v222, v222
	v_sin_f32_e32 v223, v223
	s_waitcnt lgkmcnt(0)
	v_pk_mul_f32 v[216:217], v[216:217], v[220:221]
	v_pk_mul_f32 v[218:219], v[218:219], v[222:223]
	v_pk_fma_f32 v[104:105], v[104:105], v[224:225], v[216:217]
	v_pk_fma_f32 v[106:107], v[106:107], v[226:227], v[218:219]
	v_cvt_pk_bf16_f32 v108, v108, v109
	v_cvt_pk_bf16_f32 v109, v110, v111
	v_cvt_pk_bf16_f32 v110, v104, v105
	v_cvt_pk_bf16_f32 v111, v106, v107
	global_store_dwordx4 v144, v[108:111], s[16:17]
	v_pk_mul_f32 v[100:101], v[100:101], v[198:199] op_sel_hi:[1,0]
	v_pk_mul_f32 v[102:103], v[102:103], v[198:199] op_sel_hi:[1,0]
	v_pk_mul_f32 v[96:97], v[96:97], v[198:199] op_sel_hi:[1,0]
	v_pk_mul_f32 v[98:99], v[98:99], v[198:199] op_sel_hi:[1,0]
	v_cvt_pk_bf16_f32 v100, v100, v101
	v_cvt_pk_bf16_f32 v101, v102, v103
	v_cvt_pk_bf16_f32 v102, v96, v97
	v_cvt_pk_bf16_f32 v103, v98, v99
	global_store_dwordx4 v144, v[100:103], s[16:17] offset:256
	v_add_u32_e32 v104, 0xc000, v211
	v_pk_mul_f32 v[92:93], v[92:93], v[210:211] op_sel_hi:[1,0]
	v_pk_mul_f32 v[94:95], v[94:95], v[210:211] op_sel_hi:[1,0]
	v_pk_mul_f32 v[88:89], v[88:89], v[210:211] op_sel_hi:[1,0]
	v_pk_mul_f32 v[90:91], v[90:91], v[210:211] op_sel_hi:[1,0]
	v_mov_b32_e32 v199, s55
	v_cndmask_b32_e64 v199, v203, v199, s[10:11]
	v_cvt_f32_ubyte0_e32 v199, v199
	v_mul_f32_e32 v199, v174, v199
	ds_bpermute_b32 v216, v213, v92
	ds_bpermute_b32 v217, v213, v93
	ds_bpermute_b32 v218, v213, v94
	ds_bpermute_b32 v219, v213, v95
	v_mul_f32_e32 v220, 0x3e22f983, v199
	v_mul_f32_e32 v221, 0x3d4e2601, v199
	v_mul_f32_e32 v222, 0x3c826136, v199
	v_mul_f32_e32 v223, 0x3ba4eb34, v199
	v_cos_f32_e32 v224, v220
	v_cos_f32_e32 v225, v221
	v_cos_f32_e32 v226, v222
	v_cos_f32_e32 v227, v223
	v_sin_f32_e32 v220, v220
	v_sin_f32_e32 v221, v221
	v_sin_f32_e32 v222, v222
	v_sin_f32_e32 v223, v223
	s_waitcnt lgkmcnt(0)
	v_pk_mul_f32 v[216:217], v[216:217], v[220:221]
	v_pk_mul_f32 v[218:219], v[218:219], v[222:223]
	v_pk_fma_f32 v[92:93], v[92:93], v[224:225], v[216:217]
	v_pk_fma_f32 v[94:95], v[94:95], v[226:227], v[218:219]
	ds_bpermute_b32 v216, v213, v88
	ds_bpermute_b32 v217, v213, v89
	ds_bpermute_b32 v218, v213, v90
	ds_bpermute_b32 v219, v213, v91
	v_mul_f32_e32 v220, 0x3ad09b8a, v199
	v_mul_f32_e32 v221, 0x3a03ef5d, v199
	v_mul_f32_e32 v222, 0x3926e2d4, v199
	v_mul_f32_e32 v223, 0x38531894, v199
	v_cos_f32_e32 v224, v220
	v_cos_f32_e32 v225, v221
	v_cos_f32_e32 v226, v222
	v_cos_f32_e32 v227, v223
	v_sin_f32_e32 v220, v220
	v_sin_f32_e32 v221, v221
	v_sin_f32_e32 v222, v222
	v_sin_f32_e32 v223, v223
	s_waitcnt lgkmcnt(0)
	v_pk_mul_f32 v[216:217], v[216:217], v[220:221]
	v_pk_mul_f32 v[218:219], v[218:219], v[222:223]
	v_pk_fma_f32 v[88:89], v[88:89], v[224:225], v[216:217]
	v_pk_fma_f32 v[90:91], v[90:91], v[226:227], v[218:219]
	v_cvt_pk_bf16_f32 v92, v92, v93
	v_cvt_pk_bf16_f32 v93, v94, v95
	v_cvt_pk_bf16_f32 v94, v88, v89
	v_cvt_pk_bf16_f32 v95, v90, v91
	global_store_dwordx4 v104, v[92:95], s[16:17]
	v_pk_mul_f32 v[84:85], v[84:85], v[210:211] op_sel_hi:[1,0]
	v_pk_mul_f32 v[86:87], v[86:87], v[210:211] op_sel_hi:[1,0]
	v_pk_mul_f32 v[80:81], v[80:81], v[210:211] op_sel_hi:[1,0]
	v_pk_mul_f32 v[82:83], v[82:83], v[210:211] op_sel_hi:[1,0]
	v_cvt_pk_bf16_f32 v84, v84, v85
	v_cvt_pk_bf16_f32 v85, v86, v87
	v_cvt_pk_bf16_f32 v86, v80, v81
	v_cvt_pk_bf16_f32 v87, v82, v83
	global_store_dwordx4 v104, v[84:87], s[16:17] offset:256
	v_add_u32_e32 v88, 0x12000, v211
	v_pk_mul_f32 v[76:77], v[76:77], v[212:213] op_sel_hi:[1,0]
	v_pk_mul_f32 v[78:79], v[78:79], v[212:213] op_sel_hi:[1,0]
	v_pk_mul_f32 v[72:73], v[72:73], v[212:213] op_sel_hi:[1,0]
	v_pk_mul_f32 v[74:75], v[74:75], v[212:213] op_sel_hi:[1,0]
	v_mov_b32_e32 v199, s55
	v_cndmask_b32_e64 v199, v204, v199, s[10:11]
	v_cvt_f32_ubyte0_e32 v199, v199
	v_mul_f32_e32 v199, v174, v199
	ds_bpermute_b32 v216, v213, v76
	ds_bpermute_b32 v217, v213, v77
	ds_bpermute_b32 v218, v213, v78
	ds_bpermute_b32 v219, v213, v79
	v_mul_f32_e32 v220, 0x3e22f983, v199
	v_mul_f32_e32 v221, 0x3d4e2601, v199
	v_mul_f32_e32 v222, 0x3c826136, v199
	v_mul_f32_e32 v223, 0x3ba4eb34, v199
	v_cos_f32_e32 v224, v220
	v_cos_f32_e32 v225, v221
	v_cos_f32_e32 v226, v222
	v_cos_f32_e32 v227, v223
	v_sin_f32_e32 v220, v220
	v_sin_f32_e32 v221, v221
	v_sin_f32_e32 v222, v222
	v_sin_f32_e32 v223, v223
	s_waitcnt lgkmcnt(0)
	v_pk_mul_f32 v[216:217], v[216:217], v[220:221]
	v_pk_mul_f32 v[218:219], v[218:219], v[222:223]
	v_pk_fma_f32 v[76:77], v[76:77], v[224:225], v[216:217]
	v_pk_fma_f32 v[78:79], v[78:79], v[226:227], v[218:219]
	ds_bpermute_b32 v216, v213, v72
	ds_bpermute_b32 v217, v213, v73
	ds_bpermute_b32 v218, v213, v74
	ds_bpermute_b32 v219, v213, v75
	v_mul_f32_e32 v220, 0x3ad09b8a, v199
	v_mul_f32_e32 v221, 0x3a03ef5d, v199
	v_mul_f32_e32 v222, 0x3926e2d4, v199
	v_mul_f32_e32 v223, 0x38531894, v199
	v_cos_f32_e32 v224, v220
	v_cos_f32_e32 v225, v221
	v_cos_f32_e32 v226, v222
	v_cos_f32_e32 v227, v223
	v_sin_f32_e32 v220, v220
	v_sin_f32_e32 v221, v221
	v_sin_f32_e32 v222, v222
	v_sin_f32_e32 v223, v223
	s_waitcnt lgkmcnt(0)
	v_pk_mul_f32 v[216:217], v[216:217], v[220:221]
	v_pk_mul_f32 v[218:219], v[218:219], v[222:223]
	v_pk_fma_f32 v[72:73], v[72:73], v[224:225], v[216:217]
	v_pk_fma_f32 v[74:75], v[74:75], v[226:227], v[218:219]
	v_cvt_pk_bf16_f32 v76, v76, v77
	v_cvt_pk_bf16_f32 v77, v78, v79
	v_cvt_pk_bf16_f32 v78, v72, v73
	v_cvt_pk_bf16_f32 v79, v74, v75
	global_store_dwordx4 v88, v[76:79], s[16:17]
	v_pk_mul_f32 v[68:69], v[68:69], v[212:213] op_sel_hi:[1,0]
	v_pk_mul_f32 v[70:71], v[70:71], v[212:213] op_sel_hi:[1,0]
	v_pk_mul_f32 v[64:65], v[64:65], v[212:213] op_sel_hi:[1,0]
	v_pk_mul_f32 v[66:67], v[66:67], v[212:213] op_sel_hi:[1,0]
	v_cvt_pk_bf16_f32 v68, v68, v69
	v_cvt_pk_bf16_f32 v69, v70, v71
	v_cvt_pk_bf16_f32 v70, v64, v65
	v_cvt_pk_bf16_f32 v71, v66, v67
	global_store_dwordx4 v88, v[68:71], s[16:17] offset:256
	s_mov_b32 s55, s7
	s_waitcnt vmcnt(8)
	v_pk_add_f32 v[112:113], v[112:113], v[114:115]
	v_pk_add_f32 v[116:117], v[116:117], v[118:119]
	v_pk_add_f32 v[120:121], v[120:121], v[122:123]
	v_pk_add_f32 v[112:113], v[112:113], v[116:117]
	v_pk_add_f32 v[112:113], v[112:113], v[120:121]
	v_add_f32_e32 v112, v112, v113
	v_fmamk_f32 v112, v112, 0x3b2aaaab, v208
	v_pk_add_f32 v[132:133], v[132:133], v[134:135]
	v_pk_add_f32 v[136:137], v[136:137], v[138:139]
	v_pk_add_f32 v[140:141], v[140:141], v[142:143]
	v_pk_add_f32 v[132:133], v[132:133], v[136:137]
	v_pk_add_f32 v[132:133], v[132:133], v[140:141]
	v_add_f32_e32 v132, v132, v133
	v_fmamk_f32 v132, v132, 0x3b2aaaab, v208
	v_pk_add_f32 v[152:153], v[152:153], v[154:155]
	v_pk_add_f32 v[156:157], v[156:157], v[158:159]
	v_pk_add_f32 v[160:161], v[160:161], v[162:163]
	v_pk_add_f32 v[152:153], v[152:153], v[156:157]
	v_pk_add_f32 v[152:153], v[152:153], v[160:161]
	v_add_f32_e32 v152, v152, v153
	v_fmamk_f32 v152, v152, 0x3b2aaaab, v208
	v_pk_add_f32 v[184:185], v[184:185], v[186:187]
	v_pk_add_f32 v[188:189], v[188:189], v[190:191]
	v_pk_add_f32 v[192:193], v[192:193], v[194:195]
	v_pk_add_f32 v[184:185], v[184:185], v[188:189]
	v_pk_add_f32 v[184:185], v[184:185], v[192:193]
	v_add_f32_e32 v184, v184, v185
	v_fmamk_f32 v184, v184, 0x3b2aaaab, v208
	v_rsq_f32_e32 v196, v112
	v_rsq_f32_e32 v198, v132
	v_rsq_f32_e32 v210, v152
	v_rsq_f32_e32 v212, v184
	s_nop 0
	v_mul_f32_e32 v196, 0x3e16c740, v196
	v_mul_f32_e32 v198, 0x3e16c740, v198
	v_mul_f32_e32 v210, 0x3e16c740, v210
	v_mul_f32_e32 v212, 0x3e16c740, v212
	v_add_u32_e32 v72, 0x30000, v211
	v_pk_mul_f32 v[60:61], v[60:61], v[196:197] op_sel_hi:[1,0]
	v_pk_mul_f32 v[62:63], v[62:63], v[196:197] op_sel_hi:[1,0]
	v_pk_mul_f32 v[56:57], v[56:57], v[196:197] op_sel_hi:[1,0]
	v_pk_mul_f32 v[58:59], v[58:59], v[196:197] op_sel_hi:[1,0]
	v_mov_b32_e32 v199, s55
	v_cndmask_b32_e64 v199, v200, v199, s[10:11]
	v_cvt_f32_ubyte0_e32 v199, v199
	v_mul_f32_e32 v199, v174, v199
	ds_bpermute_b32 v216, v213, v60
	ds_bpermute_b32 v217, v213, v61
	ds_bpermute_b32 v218, v213, v62
	ds_bpermute_b32 v219, v213, v63
	v_mul_f32_e32 v220, 0x3e22f983, v199
	v_mul_f32_e32 v221, 0x3d4e2601, v199
	v_mul_f32_e32 v222, 0x3c826136, v199
	v_mul_f32_e32 v223, 0x3ba4eb34, v199
	v_cos_f32_e32 v224, v220
	v_cos_f32_e32 v225, v221
	v_cos_f32_e32 v226, v222
	v_cos_f32_e32 v227, v223
	v_sin_f32_e32 v220, v220
	v_sin_f32_e32 v221, v221
	v_sin_f32_e32 v222, v222
	v_sin_f32_e32 v223, v223
	s_waitcnt lgkmcnt(0)
	v_pk_mul_f32 v[216:217], v[216:217], v[220:221]
	v_pk_mul_f32 v[218:219], v[218:219], v[222:223]
	v_pk_fma_f32 v[60:61], v[60:61], v[224:225], v[216:217]
	v_pk_fma_f32 v[62:63], v[62:63], v[226:227], v[218:219]
	ds_bpermute_b32 v216, v213, v56
	ds_bpermute_b32 v217, v213, v57
	ds_bpermute_b32 v218, v213, v58
	ds_bpermute_b32 v219, v213, v59
	v_mul_f32_e32 v220, 0x3ad09b8a, v199
	v_mul_f32_e32 v221, 0x3a03ef5d, v199
	v_mul_f32_e32 v222, 0x3926e2d4, v199
	v_mul_f32_e32 v223, 0x38531894, v199
	v_cos_f32_e32 v224, v220
	v_cos_f32_e32 v225, v221
	v_cos_f32_e32 v226, v222
	v_cos_f32_e32 v227, v223
	v_sin_f32_e32 v220, v220
	v_sin_f32_e32 v221, v221
	v_sin_f32_e32 v222, v222
	v_sin_f32_e32 v223, v223
	s_waitcnt lgkmcnt(0)
	v_pk_mul_f32 v[216:217], v[216:217], v[220:221]
	v_pk_mul_f32 v[218:219], v[218:219], v[222:223]
	v_pk_fma_f32 v[56:57], v[56:57], v[224:225], v[216:217]
	v_pk_fma_f32 v[58:59], v[58:59], v[226:227], v[218:219]
	v_cvt_pk_bf16_f32 v60, v60, v61
	v_cvt_pk_bf16_f32 v61, v62, v63
	v_cvt_pk_bf16_f32 v62, v56, v57
	v_cvt_pk_bf16_f32 v63, v58, v59
	global_store_dwordx4 v72, v[60:63], s[16:17]
	v_pk_mul_f32 v[52:53], v[52:53], v[196:197] op_sel_hi:[1,0]
	v_pk_mul_f32 v[54:55], v[54:55], v[196:197] op_sel_hi:[1,0]
	v_pk_mul_f32 v[48:49], v[48:49], v[196:197] op_sel_hi:[1,0]
	v_pk_mul_f32 v[50:51], v[50:51], v[196:197] op_sel_hi:[1,0]
	v_cvt_pk_bf16_f32 v52, v52, v53
	v_cvt_pk_bf16_f32 v53, v54, v55
	v_cvt_pk_bf16_f32 v54, v48, v49
	v_cvt_pk_bf16_f32 v55, v50, v51
	global_store_dwordx4 v72, v[52:55], s[16:17] offset:256
	v_add_u32_e32 v56, 0x36000, v211
	v_pk_mul_f32 v[44:45], v[44:45], v[198:199] op_sel_hi:[1,0]
	v_pk_mul_f32 v[46:47], v[46:47], v[198:199] op_sel_hi:[1,0]
	v_pk_mul_f32 v[40:41], v[40:41], v[198:199] op_sel_hi:[1,0]
	v_pk_mul_f32 v[42:43], v[42:43], v[198:199] op_sel_hi:[1,0]
	v_mov_b32_e32 v199, s55
	v_cndmask_b32_e64 v199, v202, v199, s[10:11]
	v_cvt_f32_ubyte0_e32 v199, v199
	v_mul_f32_e32 v199, v174, v199
	ds_bpermute_b32 v216, v213, v44
	ds_bpermute_b32 v217, v213, v45
	ds_bpermute_b32 v218, v213, v46
	ds_bpermute_b32 v219, v213, v47
	v_mul_f32_e32 v220, 0x3e22f983, v199
	v_mul_f32_e32 v221, 0x3d4e2601, v199
	v_mul_f32_e32 v222, 0x3c826136, v199
	v_mul_f32_e32 v223, 0x3ba4eb34, v199
	v_cos_f32_e32 v224, v220
	v_cos_f32_e32 v225, v221
	v_cos_f32_e32 v226, v222
	v_cos_f32_e32 v227, v223
	v_sin_f32_e32 v220, v220
	v_sin_f32_e32 v221, v221
	v_sin_f32_e32 v222, v222
	v_sin_f32_e32 v223, v223
	s_waitcnt lgkmcnt(0)
	v_pk_mul_f32 v[216:217], v[216:217], v[220:221]
	v_pk_mul_f32 v[218:219], v[218:219], v[222:223]
	v_pk_fma_f32 v[44:45], v[44:45], v[224:225], v[216:217]
	v_pk_fma_f32 v[46:47], v[46:47], v[226:227], v[218:219]
	ds_bpermute_b32 v216, v213, v40
	ds_bpermute_b32 v217, v213, v41
	ds_bpermute_b32 v218, v213, v42
	ds_bpermute_b32 v219, v213, v43
	v_mul_f32_e32 v220, 0x3ad09b8a, v199
	v_mul_f32_e32 v221, 0x3a03ef5d, v199
	v_mul_f32_e32 v222, 0x3926e2d4, v199
	v_mul_f32_e32 v223, 0x38531894, v199
	v_cos_f32_e32 v224, v220
	v_cos_f32_e32 v225, v221
	v_cos_f32_e32 v226, v222
	v_cos_f32_e32 v227, v223
	v_sin_f32_e32 v220, v220
	v_sin_f32_e32 v221, v221
	v_sin_f32_e32 v222, v222
	v_sin_f32_e32 v223, v223
	s_waitcnt lgkmcnt(0)
	v_pk_mul_f32 v[216:217], v[216:217], v[220:221]
	v_pk_mul_f32 v[218:219], v[218:219], v[222:223]
	v_pk_fma_f32 v[40:41], v[40:41], v[224:225], v[216:217]
	v_pk_fma_f32 v[42:43], v[42:43], v[226:227], v[218:219]
	v_cvt_pk_bf16_f32 v44, v44, v45
	v_cvt_pk_bf16_f32 v45, v46, v47
	v_cvt_pk_bf16_f32 v46, v40, v41
	v_cvt_pk_bf16_f32 v47, v42, v43
	global_store_dwordx4 v56, v[44:47], s[16:17]
	v_pk_mul_f32 v[36:37], v[36:37], v[198:199] op_sel_hi:[1,0]
	v_pk_mul_f32 v[38:39], v[38:39], v[198:199] op_sel_hi:[1,0]
	v_pk_mul_f32 v[32:33], v[32:33], v[198:199] op_sel_hi:[1,0]
	v_pk_mul_f32 v[34:35], v[34:35], v[198:199] op_sel_hi:[1,0]
	v_cvt_pk_bf16_f32 v36, v36, v37
	v_cvt_pk_bf16_f32 v37, v38, v39
	v_cvt_pk_bf16_f32 v38, v32, v33
	v_cvt_pk_bf16_f32 v39, v34, v35
	global_store_dwordx4 v56, v[36:39], s[16:17] offset:256
	v_add_u32_e32 v40, 0x3c000, v211
	v_pk_mul_f32 v[28:29], v[28:29], v[210:211] op_sel_hi:[1,0]
	v_pk_mul_f32 v[30:31], v[30:31], v[210:211] op_sel_hi:[1,0]
	v_pk_mul_f32 v[24:25], v[24:25], v[210:211] op_sel_hi:[1,0]
	v_pk_mul_f32 v[26:27], v[26:27], v[210:211] op_sel_hi:[1,0]
	v_mov_b32_e32 v199, s55
	v_cndmask_b32_e64 v199, v203, v199, s[10:11]
	v_cvt_f32_ubyte0_e32 v199, v199
	v_mul_f32_e32 v199, v174, v199
	ds_bpermute_b32 v216, v213, v28
	ds_bpermute_b32 v217, v213, v29
	ds_bpermute_b32 v218, v213, v30
	ds_bpermute_b32 v219, v213, v31
	v_mul_f32_e32 v220, 0x3e22f983, v199
	v_mul_f32_e32 v221, 0x3d4e2601, v199
	v_mul_f32_e32 v222, 0x3c826136, v199
	v_mul_f32_e32 v223, 0x3ba4eb34, v199
	v_cos_f32_e32 v224, v220
	v_cos_f32_e32 v225, v221
	v_cos_f32_e32 v226, v222
	v_cos_f32_e32 v227, v223
	v_sin_f32_e32 v220, v220
	v_sin_f32_e32 v221, v221
	v_sin_f32_e32 v222, v222
	v_sin_f32_e32 v223, v223
	s_waitcnt lgkmcnt(0)
	v_pk_mul_f32 v[216:217], v[216:217], v[220:221]
	v_pk_mul_f32 v[218:219], v[218:219], v[222:223]
	v_pk_fma_f32 v[28:29], v[28:29], v[224:225], v[216:217]
	v_pk_fma_f32 v[30:31], v[30:31], v[226:227], v[218:219]
	ds_bpermute_b32 v216, v213, v24
	ds_bpermute_b32 v217, v213, v25
	ds_bpermute_b32 v218, v213, v26
	ds_bpermute_b32 v219, v213, v27
	v_mul_f32_e32 v220, 0x3ad09b8a, v199
	v_mul_f32_e32 v221, 0x3a03ef5d, v199
	v_mul_f32_e32 v222, 0x3926e2d4, v199
	v_mul_f32_e32 v223, 0x38531894, v199
	v_cos_f32_e32 v224, v220
	v_cos_f32_e32 v225, v221
	v_cos_f32_e32 v226, v222
	v_cos_f32_e32 v227, v223
	v_sin_f32_e32 v220, v220
	v_sin_f32_e32 v221, v221
	v_sin_f32_e32 v222, v222
	v_sin_f32_e32 v223, v223
	s_waitcnt lgkmcnt(0)
	v_pk_mul_f32 v[216:217], v[216:217], v[220:221]
	v_pk_mul_f32 v[218:219], v[218:219], v[222:223]
	v_pk_fma_f32 v[24:25], v[24:25], v[224:225], v[216:217]
	v_pk_fma_f32 v[26:27], v[26:27], v[226:227], v[218:219]
	v_cvt_pk_bf16_f32 v28, v28, v29
	v_cvt_pk_bf16_f32 v29, v30, v31
	v_cvt_pk_bf16_f32 v30, v24, v25
	v_cvt_pk_bf16_f32 v31, v26, v27
	global_store_dwordx4 v40, v[28:31], s[16:17]
	v_pk_mul_f32 v[20:21], v[20:21], v[210:211] op_sel_hi:[1,0]
	v_pk_mul_f32 v[22:23], v[22:23], v[210:211] op_sel_hi:[1,0]
	v_pk_mul_f32 v[16:17], v[16:17], v[210:211] op_sel_hi:[1,0]
	v_pk_mul_f32 v[18:19], v[18:19], v[210:211] op_sel_hi:[1,0]
	v_cvt_pk_bf16_f32 v20, v20, v21
	v_cvt_pk_bf16_f32 v21, v22, v23
	v_cvt_pk_bf16_f32 v22, v16, v17
	v_cvt_pk_bf16_f32 v23, v18, v19
	global_store_dwordx4 v40, v[20:23], s[16:17] offset:256
	v_add_u32_e32 v24, 0x42000, v211
	v_pk_mul_f32 v[12:13], v[12:13], v[212:213] op_sel_hi:[1,0]
	v_pk_mul_f32 v[14:15], v[14:15], v[212:213] op_sel_hi:[1,0]
	v_pk_mul_f32 v[8:9], v[8:9], v[212:213] op_sel_hi:[1,0]
	v_pk_mul_f32 v[10:11], v[10:11], v[212:213] op_sel_hi:[1,0]
	v_mov_b32_e32 v199, s55
	v_cndmask_b32_e64 v199, v204, v199, s[10:11]
	v_cvt_f32_ubyte0_e32 v199, v199
	v_mul_f32_e32 v199, v174, v199
	ds_bpermute_b32 v216, v213, v12
	ds_bpermute_b32 v217, v213, v13
	ds_bpermute_b32 v218, v213, v14
	ds_bpermute_b32 v219, v213, v15
	v_mul_f32_e32 v220, 0x3e22f983, v199
	v_mul_f32_e32 v221, 0x3d4e2601, v199
	v_mul_f32_e32 v222, 0x3c826136, v199
	v_mul_f32_e32 v223, 0x3ba4eb34, v199
	v_cos_f32_e32 v224, v220
	v_cos_f32_e32 v225, v221
	v_cos_f32_e32 v226, v222
	v_cos_f32_e32 v227, v223
	v_sin_f32_e32 v220, v220
	v_sin_f32_e32 v221, v221
	v_sin_f32_e32 v222, v222
	v_sin_f32_e32 v223, v223
	s_waitcnt lgkmcnt(0)
	v_pk_mul_f32 v[216:217], v[216:217], v[220:221]
	v_pk_mul_f32 v[218:219], v[218:219], v[222:223]
	v_pk_fma_f32 v[12:13], v[12:13], v[224:225], v[216:217]
	v_pk_fma_f32 v[14:15], v[14:15], v[226:227], v[218:219]
	ds_bpermute_b32 v216, v213, v8
	ds_bpermute_b32 v217, v213, v9
	ds_bpermute_b32 v218, v213, v10
	ds_bpermute_b32 v219, v213, v11
	v_mul_f32_e32 v220, 0x3ad09b8a, v199
	v_mul_f32_e32 v221, 0x3a03ef5d, v199
	v_mul_f32_e32 v222, 0x3926e2d4, v199
	v_mul_f32_e32 v223, 0x38531894, v199
	v_cos_f32_e32 v224, v220
	v_cos_f32_e32 v225, v221
	v_cos_f32_e32 v226, v222
	v_cos_f32_e32 v227, v223
	v_sin_f32_e32 v220, v220
	v_sin_f32_e32 v221, v221
	v_sin_f32_e32 v222, v222
	v_sin_f32_e32 v223, v223
	s_waitcnt lgkmcnt(0)
	v_pk_mul_f32 v[216:217], v[216:217], v[220:221]
	v_pk_mul_f32 v[218:219], v[218:219], v[222:223]
	v_pk_fma_f32 v[8:9], v[8:9], v[224:225], v[216:217]
	v_pk_fma_f32 v[10:11], v[10:11], v[226:227], v[218:219]
	v_cvt_pk_bf16_f32 v12, v12, v13
	v_cvt_pk_bf16_f32 v13, v14, v15
	v_cvt_pk_bf16_f32 v14, v8, v9
	v_cvt_pk_bf16_f32 v15, v10, v11
	global_store_dwordx4 v24, v[12:15], s[16:17]
	v_pk_mul_f32 v[4:5], v[4:5], v[212:213] op_sel_hi:[1,0]
	v_pk_mul_f32 v[6:7], v[6:7], v[212:213] op_sel_hi:[1,0]
	v_pk_mul_f32 v[0:1], v[0:1], v[212:213] op_sel_hi:[1,0]
	v_pk_mul_f32 v[2:3], v[2:3], v[212:213] op_sel_hi:[1,0]
	v_cvt_pk_bf16_f32 v4, v4, v5
	v_cvt_pk_bf16_f32 v5, v6, v7
	v_cvt_pk_bf16_f32 v6, v0, v1
	v_cvt_pk_bf16_f32 v7, v2, v3
	global_store_dwordx4 v24, v[4:7], s[16:17] offset:256
	s_branch .Lq2_end
.Lq2_v1:
	v_pk_mul_f32 v[148:149], v[148:149], v[196:197] op_sel_hi:[1,0]
	v_pk_mul_f32 v[150:151], v[150:151], v[196:197] op_sel_hi:[1,0]
	v_pk_mul_f32 v[144:145], v[144:145], v[196:197] op_sel_hi:[1,0]
	v_pk_mul_f32 v[146:147], v[146:147], v[196:197] op_sel_hi:[1,0]
	v_cvt_pk_bf16_f32 v148, v148, v149
	v_cvt_pk_bf16_f32 v149, v150, v151
	v_cvt_pk_bf16_f32 v150, v144, v145
	v_cvt_pk_bf16_f32 v151, v146, v147
	global_store_dwordx4 v211, v[148:151], s[16:17]
	v_pk_mul_f32 v[128:129], v[128:129], v[196:197] op_sel_hi:[1,0]
	v_pk_mul_f32 v[130:131], v[130:131], v[196:197] op_sel_hi:[1,0]
	v_pk_mul_f32 v[124:125], v[124:125], v[196:197] op_sel_hi:[1,0]
	v_pk_mul_f32 v[126:127], v[126:127], v[196:197] op_sel_hi:[1,0]
	v_mov_b32_e32 v199, s55
	v_cndmask_b32_e64 v199, v200, v199, s[10:11]
	v_cvt_f32_ubyte0_e32 v199, v199
	v_mul_f32_e32 v199, v174, v199
	ds_bpermute_b32 v216, v213, v128
	ds_bpermute_b32 v217, v213, v129
	ds_bpermute_b32 v218, v213, v130
	ds_bpermute_b32 v219, v213, v131
	v_mul_f32_e32 v220, 0x3e22f983, v199
	v_mul_f32_e32 v221, 0x3d4e2601, v199
	v_mul_f32_e32 v222, 0x3c826136, v199
	v_mul_f32_e32 v223, 0x3ba4eb34, v199
	v_cos_f32_e32 v224, v220
	v_cos_f32_e32 v225, v221
	v_cos_f32_e32 v226, v222
	v_cos_f32_e32 v227, v223
	v_sin_f32_e32 v220, v220
	v_sin_f32_e32 v221, v221
	v_sin_f32_e32 v222, v222
	v_sin_f32_e32 v223, v223
	s_waitcnt lgkmcnt(0)
	v_pk_mul_f32 v[216:217], v[216:217], v[220:221]
	v_pk_mul_f32 v[218:219], v[218:219], v[222:223]
	v_pk_fma_f32 v[128:129], v[128:129], v[224:225], v[216:217]
	v_pk_fma_f32 v[130:131], v[130:131], v[226:227], v[218:219]
	ds_bpermute_b32 v216, v213, v124
	ds_bpermute_b32 v217, v213, v125
	ds_bpermute_b32 v218, v213, v126
	ds_bpermute_b32 v219, v213, v127
	v_mul_f32_e32 v220, 0x3ad09b8a, v199
	v_mul_f32_e32 v221, 0x3a03ef5d, v199
	v_mul_f32_e32 v222, 0x3926e2d4, v199
	v_mul_f32_e32 v223, 0x38531894, v199
	v_cos_f32_e32 v224, v220
	v_cos_f32_e32 v225, v221
	v_cos_f32_e32 v226, v222
	v_cos_f32_e32 v227, v223
	v_sin_f32_e32 v220, v220
	v_sin_f32_e32 v221, v221
	v_sin_f32_e32 v222, v222
	v_sin_f32_e32 v223, v223
	s_waitcnt lgkmcnt(0)
	v_pk_mul_f32 v[216:217], v[216:217], v[220:221]
	v_pk_mul_f32 v[218:219], v[218:219], v[222:223]
	v_pk_fma_f32 v[124:125], v[124:125], v[224:225], v[216:217]
	v_pk_fma_f32 v[126:127], v[126:127], v[226:227], v[218:219]
	v_cvt_pk_bf16_f32 v128, v128, v129
	v_cvt_pk_bf16_f32 v129, v130, v131
	v_cvt_pk_bf16_f32 v130, v124, v125
	v_cvt_pk_bf16_f32 v131, v126, v127
	global_store_dwordx4 v211, v[128:131], s[16:17] offset:256
	v_add_u32_e32 v144, 0x6000, v211
	v_pk_mul_f32 v[108:109], v[108:109], v[198:199] op_sel_hi:[1,0]
	v_pk_mul_f32 v[110:111], v[110:111], v[198:199] op_sel_hi:[1,0]
	v_pk_mul_f32 v[104:105], v[104:105], v[198:199] op_sel_hi:[1,0]
	v_pk_mul_f32 v[106:107], v[106:107], v[198:199] op_sel_hi:[1,0]
	v_cvt_pk_bf16_f32 v108, v108, v109
	v_cvt_pk_bf16_f32 v109, v110, v111
	v_cvt_pk_bf16_f32 v110, v104, v105
	v_cvt_pk_bf16_f32 v111, v106, v107
	global_store_dwordx4 v144, v[108:111], s[16:17]
	v_pk_mul_f32 v[100:101], v[100:101], v[198:199] op_sel_hi:[1,0]
	v_pk_mul_f32 v[102:103], v[102:103], v[198:199] op_sel_hi:[1,0]
	v_pk_mul_f32 v[96:97], v[96:97], v[198:199] op_sel_hi:[1,0]
	v_pk_mul_f32 v[98:99], v[98:99], v[198:199] op_sel_hi:[1,0]
	v_mov_b32_e32 v199, s55
	v_cndmask_b32_e64 v199, v202, v199, s[10:11]
	v_cvt_f32_ubyte0_e32 v199, v199
	v_mul_f32_e32 v199, v174, v199
	ds_bpermute_b32 v216, v213, v100
	ds_bpermute_b32 v217, v213, v101
	ds_bpermute_b32 v218, v213, v102
	ds_bpermute_b32 v219, v213, v103
	v_mul_f32_e32 v220, 0x3e22f983, v199
	v_mul_f32_e32 v221, 0x3d4e2601, v199
	v_mul_f32_e32 v222, 0x3c826136, v199
	v_mul_f32_e32 v223, 0x3ba4eb34, v199
	v_cos_f32_e32 v224, v220
	v_cos_f32_e32 v225, v221
	v_cos_f32_e32 v226, v222
	v_cos_f32_e32 v227, v223
	v_sin_f32_e32 v220, v220
	v_sin_f32_e32 v221, v221
	v_sin_f32_e32 v222, v222
	v_sin_f32_e32 v223, v223
	s_waitcnt lgkmcnt(0)
	v_pk_mul_f32 v[216:217], v[216:217], v[220:221]
	v_pk_mul_f32 v[218:219], v[218:219], v[222:223]
	v_pk_fma_f32 v[100:101], v[100:101], v[224:225], v[216:217]
	v_pk_fma_f32 v[102:103], v[102:103], v[226:227], v[218:219]
	ds_bpermute_b32 v216, v213, v96
	ds_bpermute_b32 v217, v213, v97
	ds_bpermute_b32 v218, v213, v98
	ds_bpermute_b32 v219, v213, v99
	v_mul_f32_e32 v220, 0x3ad09b8a, v199
	v_mul_f32_e32 v221, 0x3a03ef5d, v199
	v_mul_f32_e32 v222, 0x3926e2d4, v199
	v_mul_f32_e32 v223, 0x38531894, v199
	v_cos_f32_e32 v224, v220
	v_cos_f32_e32 v225, v221
	v_cos_f32_e32 v226, v222
	v_cos_f32_e32 v227, v223
	v_sin_f32_e32 v220, v220
	v_sin_f32_e32 v221, v221
	v_sin_f32_e32 v222, v222
	v_sin_f32_e32 v223, v223
	s_waitcnt lgkmcnt(0)
	v_pk_mul_f32 v[216:217], v[216:217], v[220:221]
	v_pk_mul_f32 v[218:219], v[218:219], v[222:223]
	v_pk_fma_f32 v[96:97], v[96:97], v[224:225], v[216:217]
	v_pk_fma_f32 v[98:99], v[98:99], v[226:227], v[218:219]
	v_cvt_pk_bf16_f32 v100, v100, v101
	v_cvt_pk_bf16_f32 v101, v102, v103
	v_cvt_pk_bf16_f32 v102, v96, v97
	v_cvt_pk_bf16_f32 v103, v98, v99
	global_store_dwordx4 v144, v[100:103], s[16:17] offset:256
	v_add_u32_e32 v104, 0xc000, v211
	v_pk_mul_f32 v[92:93], v[92:93], v[210:211] op_sel_hi:[1,0]
	v_pk_mul_f32 v[94:95], v[94:95], v[210:211] op_sel_hi:[1,0]
	v_pk_mul_f32 v[88:89], v[88:89], v[210:211] op_sel_hi:[1,0]
	v_pk_mul_f32 v[90:91], v[90:91], v[210:211] op_sel_hi:[1,0]
	v_cvt_pk_bf16_f32 v92, v92, v93
	v_cvt_pk_bf16_f32 v93, v94, v95
	v_cvt_pk_bf16_f32 v94, v88, v89
	v_cvt_pk_bf16_f32 v95, v90, v91
	global_store_dwordx4 v104, v[92:95], s[16:17]
	v_pk_mul_f32 v[84:85], v[84:85], v[210:211] op_sel_hi:[1,0]
	v_pk_mul_f32 v[86:87], v[86:87], v[210:211] op_sel_hi:[1,0]
	v_pk_mul_f32 v[80:81], v[80:81], v[210:211] op_sel_hi:[1,0]
	v_pk_mul_f32 v[82:83], v[82:83], v[210:211] op_sel_hi:[1,0]
	v_mov_b32_e32 v199, s55
	v_cndmask_b32_e64 v199, v203, v199, s[10:11]
	v_cvt_f32_ubyte0_e32 v199, v199
	v_mul_f32_e32 v199, v174, v199
	ds_bpermute_b32 v216, v213, v84
	ds_bpermute_b32 v217, v213, v85
	ds_bpermute_b32 v218, v213, v86
	ds_bpermute_b32 v219, v213, v87
	v_mul_f32_e32 v220, 0x3e22f983, v199
	v_mul_f32_e32 v221, 0x3d4e2601, v199
	v_mul_f32_e32 v222, 0x3c826136, v199
	v_mul_f32_e32 v223, 0x3ba4eb34, v199
	v_cos_f32_e32 v224, v220
	v_cos_f32_e32 v225, v221
	v_cos_f32_e32 v226, v222
	v_cos_f32_e32 v227, v223
	v_sin_f32_e32 v220, v220
	v_sin_f32_e32 v221, v221
	v_sin_f32_e32 v222, v222
	v_sin_f32_e32 v223, v223
	s_waitcnt lgkmcnt(0)
	v_pk_mul_f32 v[216:217], v[216:217], v[220:221]
	v_pk_mul_f32 v[218:219], v[218:219], v[222:223]
	v_pk_fma_f32 v[84:85], v[84:85], v[224:225], v[216:217]
	v_pk_fma_f32 v[86:87], v[86:87], v[226:227], v[218:219]
	ds_bpermute_b32 v216, v213, v80
	ds_bpermute_b32 v217, v213, v81
	ds_bpermute_b32 v218, v213, v82
	ds_bpermute_b32 v219, v213, v83
	v_mul_f32_e32 v220, 0x3ad09b8a, v199
	v_mul_f32_e32 v221, 0x3a03ef5d, v199
	v_mul_f32_e32 v222, 0x3926e2d4, v199
	v_mul_f32_e32 v223, 0x38531894, v199
	v_cos_f32_e32 v224, v220
	v_cos_f32_e32 v225, v221
	v_cos_f32_e32 v226, v222
	v_cos_f32_e32 v227, v223
	v_sin_f32_e32 v220, v220
	v_sin_f32_e32 v221, v221
	v_sin_f32_e32 v222, v222
	v_sin_f32_e32 v223, v223
	s_waitcnt lgkmcnt(0)
	v_pk_mul_f32 v[216:217], v[216:217], v[220:221]
	v_pk_mul_f32 v[218:219], v[218:219], v[222:223]
	v_pk_fma_f32 v[80:81], v[80:81], v[224:225], v[216:217]
	v_pk_fma_f32 v[82:83], v[82:83], v[226:227], v[218:219]
	v_cvt_pk_bf16_f32 v84, v84, v85
	v_cvt_pk_bf16_f32 v85, v86, v87
	v_cvt_pk_bf16_f32 v86, v80, v81
	v_cvt_pk_bf16_f32 v87, v82, v83
	global_store_dwordx4 v104, v[84:87], s[16:17] offset:256
	v_add_u32_e32 v88, 0x12000, v211
	v_pk_mul_f32 v[76:77], v[76:77], v[212:213] op_sel_hi:[1,0]
	v_pk_mul_f32 v[78:79], v[78:79], v[212:213] op_sel_hi:[1,0]
	v_pk_mul_f32 v[72:73], v[72:73], v[212:213] op_sel_hi:[1,0]
	v_pk_mul_f32 v[74:75], v[74:75], v[212:213] op_sel_hi:[1,0]
	v_cvt_pk_bf16_f32 v76, v76, v77
	v_cvt_pk_bf16_f32 v77, v78, v79
	v_cvt_pk_bf16_f32 v78, v72, v73
	v_cvt_pk_bf16_f32 v79, v74, v75
	global_store_dwordx4 v88, v[76:79], s[16:17]
	v_pk_mul_f32 v[68:69], v[68:69], v[212:213] op_sel_hi:[1,0]
	v_pk_mul_f32 v[70:71], v[70:71], v[212:213] op_sel_hi:[1,0]
	v_pk_mul_f32 v[64:65], v[64:65], v[212:213] op_sel_hi:[1,0]
	v_pk_mul_f32 v[66:67], v[66:67], v[212:213] op_sel_hi:[1,0]
	v_mov_b32_e32 v199, s55
	v_cndmask_b32_e64 v199, v204, v199, s[10:11]
	v_cvt_f32_ubyte0_e32 v199, v199
	v_mul_f32_e32 v199, v174, v199
	ds_bpermute_b32 v216, v213, v68
	ds_bpermute_b32 v217, v213, v69
	ds_bpermute_b32 v218, v213, v70
	ds_bpermute_b32 v219, v213, v71
	v_mul_f32_e32 v220, 0x3e22f983, v199
	v_mul_f32_e32 v221, 0x3d4e2601, v199
	v_mul_f32_e32 v222, 0x3c826136, v199
	v_mul_f32_e32 v223, 0x3ba4eb34, v199
	v_cos_f32_e32 v224, v220
	v_cos_f32_e32 v225, v221
	v_cos_f32_e32 v226, v222
	v_cos_f32_e32 v227, v223
	v_sin_f32_e32 v220, v220
	v_sin_f32_e32 v221, v221
	v_sin_f32_e32 v222, v222
	v_sin_f32_e32 v223, v223
	s_waitcnt lgkmcnt(0)
	v_pk_mul_f32 v[216:217], v[216:217], v[220:221]
	v_pk_mul_f32 v[218:219], v[218:219], v[222:223]
	v_pk_fma_f32 v[68:69], v[68:69], v[224:225], v[216:217]
	v_pk_fma_f32 v[70:71], v[70:71], v[226:227], v[218:219]
	ds_bpermute_b32 v216, v213, v64
	ds_bpermute_b32 v217, v213, v65
	ds_bpermute_b32 v218, v213, v66
	ds_bpermute_b32 v219, v213, v67
	v_mul_f32_e32 v220, 0x3ad09b8a, v199
	v_mul_f32_e32 v221, 0x3a03ef5d, v199
	v_mul_f32_e32 v222, 0x3926e2d4, v199
	v_mul_f32_e32 v223, 0x38531894, v199
	v_cos_f32_e32 v224, v220
	v_cos_f32_e32 v225, v221
	v_cos_f32_e32 v226, v222
	v_cos_f32_e32 v227, v223
	v_sin_f32_e32 v220, v220
	v_sin_f32_e32 v221, v221
	v_sin_f32_e32 v222, v222
	v_sin_f32_e32 v223, v223
	s_waitcnt lgkmcnt(0)
	v_pk_mul_f32 v[216:217], v[216:217], v[220:221]
	v_pk_mul_f32 v[218:219], v[218:219], v[222:223]
	v_pk_fma_f32 v[64:65], v[64:65], v[224:225], v[216:217]
	v_pk_fma_f32 v[66:67], v[66:67], v[226:227], v[218:219]
	v_cvt_pk_bf16_f32 v68, v68, v69
	v_cvt_pk_bf16_f32 v69, v70, v71
	v_cvt_pk_bf16_f32 v70, v64, v65
	v_cvt_pk_bf16_f32 v71, v66, v67
	global_store_dwordx4 v88, v[68:71], s[16:17] offset:256
	s_mov_b32 s55, s7
	s_waitcnt vmcnt(8)
	v_pk_add_f32 v[112:113], v[112:113], v[114:115]
	v_pk_add_f32 v[116:117], v[116:117], v[118:119]
	v_pk_add_f32 v[120:121], v[120:121], v[122:123]
	v_pk_add_f32 v[112:113], v[112:113], v[116:117]
	v_pk_add_f32 v[112:113], v[112:113], v[120:121]
	v_add_f32_e32 v112, v112, v113
	v_fmamk_f32 v112, v112, 0x3b2aaaab, v208
	v_pk_add_f32 v[132:133], v[132:133], v[134:135]
	v_pk_add_f32 v[136:137], v[136:137], v[138:139]
	v_pk_add_f32 v[140:141], v[140:141], v[142:143]
	v_pk_add_f32 v[132:133], v[132:133], v[136:137]
	v_pk_add_f32 v[132:133], v[132:133], v[140:141]
	v_add_f32_e32 v132, v132, v133
	v_fmamk_f32 v132, v132, 0x3b2aaaab, v208
	v_pk_add_f32 v[152:153], v[152:153], v[154:155]
	v_pk_add_f32 v[156:157], v[156:157], v[158:159]
	v_pk_add_f32 v[160:161], v[160:161], v[162:163]
	v_pk_add_f32 v[152:153], v[152:153], v[156:157]
	v_pk_add_f32 v[152:153], v[152:153], v[160:161]
	v_add_f32_e32 v152, v152, v153
	v_fmamk_f32 v152, v152, 0x3b2aaaab, v208
	v_pk_add_f32 v[184:185], v[184:185], v[186:187]
	v_pk_add_f32 v[188:189], v[188:189], v[190:191]
	v_pk_add_f32 v[192:193], v[192:193], v[194:195]
	v_pk_add_f32 v[184:185], v[184:185], v[188:189]
	v_pk_add_f32 v[184:185], v[184:185], v[192:193]
	v_add_f32_e32 v184, v184, v185
	v_fmamk_f32 v184, v184, 0x3b2aaaab, v208
	v_rsq_f32_e32 v196, v112
	v_rsq_f32_e32 v198, v132
	v_rsq_f32_e32 v210, v152
	v_rsq_f32_e32 v212, v184
	s_nop 0
	v_mul_f32_e32 v196, 0x3e16c740, v196
	v_mul_f32_e32 v198, 0x3e16c740, v198
	v_mul_f32_e32 v210, 0x3e16c740, v210
	v_mul_f32_e32 v212, 0x3e16c740, v212
	v_add_u32_e32 v72, 0x30000, v211
	v_pk_mul_f32 v[60:61], v[60:61], v[196:197] op_sel_hi:[1,0]
	v_pk_mul_f32 v[62:63], v[62:63], v[196:197] op_sel_hi:[1,0]
	v_pk_mul_f32 v[56:57], v[56:57], v[196:197] op_sel_hi:[1,0]
	v_pk_mul_f32 v[58:59], v[58:59], v[196:197] op_sel_hi:[1,0]
	v_cvt_pk_bf16_f32 v60, v60, v61
	v_cvt_pk_bf16_f32 v61, v62, v63
	v_cvt_pk_bf16_f32 v62, v56, v57
	v_cvt_pk_bf16_f32 v63, v58, v59
	global_store_dwordx4 v72, v[60:63], s[16:17]
	v_pk_mul_f32 v[52:53], v[52:53], v[196:197] op_sel_hi:[1,0]
	v_pk_mul_f32 v[54:55], v[54:55], v[196:197] op_sel_hi:[1,0]
	v_pk_mul_f32 v[48:49], v[48:49], v[196:197] op_sel_hi:[1,0]
	v_pk_mul_f32 v[50:51], v[50:51], v[196:197] op_sel_hi:[1,0]
	v_mov_b32_e32 v199, s55
	v_cndmask_b32_e64 v199, v200, v199, s[10:11]
	v_cvt_f32_ubyte0_e32 v199, v199
	v_mul_f32_e32 v199, v174, v199
	ds_bpermute_b32 v216, v213, v52
	ds_bpermute_b32 v217, v213, v53
	ds_bpermute_b32 v218, v213, v54
	ds_bpermute_b32 v219, v213, v55
	v_mul_f32_e32 v220, 0x3e22f983, v199
	v_mul_f32_e32 v221, 0x3d4e2601, v199
	v_mul_f32_e32 v222, 0x3c826136, v199
	v_mul_f32_e32 v223, 0x3ba4eb34, v199
	v_cos_f32_e32 v224, v220
	v_cos_f32_e32 v225, v221
	v_cos_f32_e32 v226, v222
	v_cos_f32_e32 v227, v223
	v_sin_f32_e32 v220, v220
	v_sin_f32_e32 v221, v221
	v_sin_f32_e32 v222, v222
	v_sin_f32_e32 v223, v223
	s_waitcnt lgkmcnt(0)
	v_pk_mul_f32 v[216:217], v[216:217], v[220:221]
	v_pk_mul_f32 v[218:219], v[218:219], v[222:223]
	v_pk_fma_f32 v[52:53], v[52:53], v[224:225], v[216:217]
	v_pk_fma_f32 v[54:55], v[54:55], v[226:227], v[218:219]
	ds_bpermute_b32 v216, v213, v48
	ds_bpermute_b32 v217, v213, v49
	ds_bpermute_b32 v218, v213, v50
	ds_bpermute_b32 v219, v213, v51
	v_mul_f32_e32 v220, 0x3ad09b8a, v199
	v_mul_f32_e32 v221, 0x3a03ef5d, v199
	v_mul_f32_e32 v222, 0x3926e2d4, v199
	v_mul_f32_e32 v223, 0x38531894, v199
	v_cos_f32_e32 v224, v220
	v_cos_f32_e32 v225, v221
	v_cos_f32_e32 v226, v222
	v_cos_f32_e32 v227, v223
	v_sin_f32_e32 v220, v220
	v_sin_f32_e32 v221, v221
	v_sin_f32_e32 v222, v222
	v_sin_f32_e32 v223, v223
	s_waitcnt lgkmcnt(0)
	v_pk_mul_f32 v[216:217], v[216:217], v[220:221]
	v_pk_mul_f32 v[218:219], v[218:219], v[222:223]
	v_pk_fma_f32 v[48:49], v[48:49], v[224:225], v[216:217]
	v_pk_fma_f32 v[50:51], v[50:51], v[226:227], v[218:219]
	v_cvt_pk_bf16_f32 v52, v52, v53
	v_cvt_pk_bf16_f32 v53, v54, v55
	v_cvt_pk_bf16_f32 v54, v48, v49
	v_cvt_pk_bf16_f32 v55, v50, v51
	global_store_dwordx4 v72, v[52:55], s[16:17] offset:256
	v_add_u32_e32 v56, 0x36000, v211
	v_pk_mul_f32 v[44:45], v[44:45], v[198:199] op_sel_hi:[1,0]
	v_pk_mul_f32 v[46:47], v[46:47], v[198:199] op_sel_hi:[1,0]
	v_pk_mul_f32 v[40:41], v[40:41], v[198:199] op_sel_hi:[1,0]
	v_pk_mul_f32 v[42:43], v[42:43], v[198:199] op_sel_hi:[1,0]
	v_cvt_pk_bf16_f32 v44, v44, v45
	v_cvt_pk_bf16_f32 v45, v46, v47
	v_cvt_pk_bf16_f32 v46, v40, v41
	v_cvt_pk_bf16_f32 v47, v42, v43
	global_store_dwordx4 v56, v[44:47], s[16:17]
	v_pk_mul_f32 v[36:37], v[36:37], v[198:199] op_sel_hi:[1,0]
	v_pk_mul_f32 v[38:39], v[38:39], v[198:199] op_sel_hi:[1,0]
	v_pk_mul_f32 v[32:33], v[32:33], v[198:199] op_sel_hi:[1,0]
	v_pk_mul_f32 v[34:35], v[34:35], v[198:199] op_sel_hi:[1,0]
	v_mov_b32_e32 v199, s55
	v_cndmask_b32_e64 v199, v202, v199, s[10:11]
	v_cvt_f32_ubyte0_e32 v199, v199
	v_mul_f32_e32 v199, v174, v199
	ds_bpermute_b32 v216, v213, v36
	ds_bpermute_b32 v217, v213, v37
	ds_bpermute_b32 v218, v213, v38
	ds_bpermute_b32 v219, v213, v39
	v_mul_f32_e32 v220, 0x3e22f983, v199
	v_mul_f32_e32 v221, 0x3d4e2601, v199
	v_mul_f32_e32 v222, 0x3c826136, v199
	v_mul_f32_e32 v223, 0x3ba4eb34, v199
	v_cos_f32_e32 v224, v220
	v_cos_f32_e32 v225, v221
	v_cos_f32_e32 v226, v222
	v_cos_f32_e32 v227, v223
	v_sin_f32_e32 v220, v220
	v_sin_f32_e32 v221, v221
	v_sin_f32_e32 v222, v222
	v_sin_f32_e32 v223, v223
	s_waitcnt lgkmcnt(0)
	v_pk_mul_f32 v[216:217], v[216:217], v[220:221]
	v_pk_mul_f32 v[218:219], v[218:219], v[222:223]
	v_pk_fma_f32 v[36:37], v[36:37], v[224:225], v[216:217]
	v_pk_fma_f32 v[38:39], v[38:39], v[226:227], v[218:219]
	ds_bpermute_b32 v216, v213, v32
	ds_bpermute_b32 v217, v213, v33
	ds_bpermute_b32 v218, v213, v34
	ds_bpermute_b32 v219, v213, v35
	v_mul_f32_e32 v220, 0x3ad09b8a, v199
	v_mul_f32_e32 v221, 0x3a03ef5d, v199
	v_mul_f32_e32 v222, 0x3926e2d4, v199
	v_mul_f32_e32 v223, 0x38531894, v199
	v_cos_f32_e32 v224, v220
	v_cos_f32_e32 v225, v221
	v_cos_f32_e32 v226, v222
	v_cos_f32_e32 v227, v223
	v_sin_f32_e32 v220, v220
	v_sin_f32_e32 v221, v221
	v_sin_f32_e32 v222, v222
	v_sin_f32_e32 v223, v223
	s_waitcnt lgkmcnt(0)
	v_pk_mul_f32 v[216:217], v[216:217], v[220:221]
	v_pk_mul_f32 v[218:219], v[218:219], v[222:223]
	v_pk_fma_f32 v[32:33], v[32:33], v[224:225], v[216:217]
	v_pk_fma_f32 v[34:35], v[34:35], v[226:227], v[218:219]
	v_cvt_pk_bf16_f32 v36, v36, v37
	v_cvt_pk_bf16_f32 v37, v38, v39
	v_cvt_pk_bf16_f32 v38, v32, v33
	v_cvt_pk_bf16_f32 v39, v34, v35
	global_store_dwordx4 v56, v[36:39], s[16:17] offset:256
	v_add_u32_e32 v40, 0x3c000, v211
	v_pk_mul_f32 v[28:29], v[28:29], v[210:211] op_sel_hi:[1,0]
	v_pk_mul_f32 v[30:31], v[30:31], v[210:211] op_sel_hi:[1,0]
	v_pk_mul_f32 v[24:25], v[24:25], v[210:211] op_sel_hi:[1,0]
	v_pk_mul_f32 v[26:27], v[26:27], v[210:211] op_sel_hi:[1,0]
	v_cvt_pk_bf16_f32 v28, v28, v29
	v_cvt_pk_bf16_f32 v29, v30, v31
	v_cvt_pk_bf16_f32 v30, v24, v25
	v_cvt_pk_bf16_f32 v31, v26, v27
	global_store_dwordx4 v40, v[28:31], s[16:17]
	v_pk_mul_f32 v[20:21], v[20:21], v[210:211] op_sel_hi:[1,0]
	v_pk_mul_f32 v[22:23], v[22:23], v[210:211] op_sel_hi:[1,0]
	v_pk_mul_f32 v[16:17], v[16:17], v[210:211] op_sel_hi:[1,0]
	v_pk_mul_f32 v[18:19], v[18:19], v[210:211] op_sel_hi:[1,0]
	v_mov_b32_e32 v199, s55
	v_cndmask_b32_e64 v199, v203, v199, s[10:11]
	v_cvt_f32_ubyte0_e32 v199, v199
	v_mul_f32_e32 v199, v174, v199
	ds_bpermute_b32 v216, v213, v20
	ds_bpermute_b32 v217, v213, v21
	ds_bpermute_b32 v218, v213, v22
	ds_bpermute_b32 v219, v213, v23
	v_mul_f32_e32 v220, 0x3e22f983, v199
	v_mul_f32_e32 v221, 0x3d4e2601, v199
	v_mul_f32_e32 v222, 0x3c826136, v199
	v_mul_f32_e32 v223, 0x3ba4eb34, v199
	v_cos_f32_e32 v224, v220
	v_cos_f32_e32 v225, v221
	v_cos_f32_e32 v226, v222
	v_cos_f32_e32 v227, v223
	v_sin_f32_e32 v220, v220
	v_sin_f32_e32 v221, v221
	v_sin_f32_e32 v222, v222
	v_sin_f32_e32 v223, v223
	s_waitcnt lgkmcnt(0)
	v_pk_mul_f32 v[216:217], v[216:217], v[220:221]
	v_pk_mul_f32 v[218:219], v[218:219], v[222:223]
	v_pk_fma_f32 v[20:21], v[20:21], v[224:225], v[216:217]
	v_pk_fma_f32 v[22:23], v[22:23], v[226:227], v[218:219]
	ds_bpermute_b32 v216, v213, v16
	ds_bpermute_b32 v217, v213, v17
	ds_bpermute_b32 v218, v213, v18
	ds_bpermute_b32 v219, v213, v19
	v_mul_f32_e32 v220, 0x3ad09b8a, v199
	v_mul_f32_e32 v221, 0x3a03ef5d, v199
	v_mul_f32_e32 v222, 0x3926e2d4, v199
	v_mul_f32_e32 v223, 0x38531894, v199
	v_cos_f32_e32 v224, v220
	v_cos_f32_e32 v225, v221
	v_cos_f32_e32 v226, v222
	v_cos_f32_e32 v227, v223
	v_sin_f32_e32 v220, v220
	v_sin_f32_e32 v221, v221
	v_sin_f32_e32 v222, v222
	v_sin_f32_e32 v223, v223
	s_waitcnt lgkmcnt(0)
	v_pk_mul_f32 v[216:217], v[216:217], v[220:221]
	v_pk_mul_f32 v[218:219], v[218:219], v[222:223]
	v_pk_fma_f32 v[16:17], v[16:17], v[224:225], v[216:217]
	v_pk_fma_f32 v[18:19], v[18:19], v[226:227], v[218:219]
	v_cvt_pk_bf16_f32 v20, v20, v21
	v_cvt_pk_bf16_f32 v21, v22, v23
	v_cvt_pk_bf16_f32 v22, v16, v17
	v_cvt_pk_bf16_f32 v23, v18, v19
	global_store_dwordx4 v40, v[20:23], s[16:17] offset:256
	v_add_u32_e32 v24, 0x42000, v211
	v_pk_mul_f32 v[12:13], v[12:13], v[212:213] op_sel_hi:[1,0]
	v_pk_mul_f32 v[14:15], v[14:15], v[212:213] op_sel_hi:[1,0]
	v_pk_mul_f32 v[8:9], v[8:9], v[212:213] op_sel_hi:[1,0]
	v_pk_mul_f32 v[10:11], v[10:11], v[212:213] op_sel_hi:[1,0]
	v_cvt_pk_bf16_f32 v12, v12, v13
	v_cvt_pk_bf16_f32 v13, v14, v15
	v_cvt_pk_bf16_f32 v14, v8, v9
	v_cvt_pk_bf16_f32 v15, v10, v11
	global_store_dwordx4 v24, v[12:15], s[16:17]
	v_pk_mul_f32 v[4:5], v[4:5], v[212:213] op_sel_hi:[1,0]
	v_pk_mul_f32 v[6:7], v[6:7], v[212:213] op_sel_hi:[1,0]
	v_pk_mul_f32 v[0:1], v[0:1], v[212:213] op_sel_hi:[1,0]
	v_pk_mul_f32 v[2:3], v[2:3], v[212:213] op_sel_hi:[1,0]
	v_mov_b32_e32 v199, s55
	v_cndmask_b32_e64 v199, v204, v199, s[10:11]
	v_cvt_f32_ubyte0_e32 v199, v199
	v_mul_f32_e32 v199, v174, v199
	ds_bpermute_b32 v216, v213, v4
	ds_bpermute_b32 v217, v213, v5
	ds_bpermute_b32 v218, v213, v6
	ds_bpermute_b32 v219, v213, v7
	v_mul_f32_e32 v220, 0x3e22f983, v199
	v_mul_f32_e32 v221, 0x3d4e2601, v199
	v_mul_f32_e32 v222, 0x3c826136, v199
	v_mul_f32_e32 v223, 0x3ba4eb34, v199
	v_cos_f32_e32 v224, v220
	v_cos_f32_e32 v225, v221
	v_cos_f32_e32 v226, v222
	v_cos_f32_e32 v227, v223
	v_sin_f32_e32 v220, v220
	v_sin_f32_e32 v221, v221
	v_sin_f32_e32 v222, v222
	v_sin_f32_e32 v223, v223
	s_waitcnt lgkmcnt(0)
	v_pk_mul_f32 v[216:217], v[216:217], v[220:221]
	v_pk_mul_f32 v[218:219], v[218:219], v[222:223]
	v_pk_fma_f32 v[4:5], v[4:5], v[224:225], v[216:217]
	v_pk_fma_f32 v[6:7], v[6:7], v[226:227], v[218:219]
	ds_bpermute_b32 v216, v213, v0
	ds_bpermute_b32 v217, v213, v1
	ds_bpermute_b32 v218, v213, v2
	ds_bpermute_b32 v219, v213, v3
	v_mul_f32_e32 v220, 0x3ad09b8a, v199
	v_mul_f32_e32 v221, 0x3a03ef5d, v199
	v_mul_f32_e32 v222, 0x3926e2d4, v199
	v_mul_f32_e32 v223, 0x38531894, v199
	v_cos_f32_e32 v224, v220
	v_cos_f32_e32 v225, v221
	v_cos_f32_e32 v226, v222
	v_cos_f32_e32 v227, v223
	v_sin_f32_e32 v220, v220
	v_sin_f32_e32 v221, v221
	v_sin_f32_e32 v222, v222
	v_sin_f32_e32 v223, v223
	s_waitcnt lgkmcnt(0)
	v_pk_mul_f32 v[216:217], v[216:217], v[220:221]
	v_pk_mul_f32 v[218:219], v[218:219], v[222:223]
	v_pk_fma_f32 v[0:1], v[0:1], v[224:225], v[216:217]
	v_pk_fma_f32 v[2:3], v[2:3], v[226:227], v[218:219]
	v_cvt_pk_bf16_f32 v4, v4, v5
	v_cvt_pk_bf16_f32 v5, v6, v7
	v_cvt_pk_bf16_f32 v6, v0, v1
	v_cvt_pk_bf16_f32 v7, v2, v3
	global_store_dwordx4 v24, v[4:7], s[16:17] offset:256

.LBB0_1110:
	s_cmp_lt_i32 s94, 7
	s_cselect_b64 s[0:1], -1, 0
	s_cmp_gt_i32 s95, 6
	s_cselect_b64 s[2:3], -1, 0
	s_and_b64 s[0:1], s[0:1], s[2:3]
	s_andn2_b64 vcc, exec, s[0:1]
	s_cbranch_vccnz .LBB0_1172
	v_readlane_b32 s0, v253, 54
	s_cmpk_lt_i32 s0, 0x2000
	v_readlane_b32 s1, v253, 55
	s_cbranch_scc0 .LBB0_1118
	v_mbcnt_lo_u32_b32 v1, -1, 0
	v_mbcnt_hi_u32_b32 v1, -1, v1
	v_and_b32_e32 v3, 64, v1
	v_add_u32_e32 v3, 64, v3
	v_xor_b32_e32 v5, 1, v1
	v_cmp_lt_i32_e32 vcc, v5, v3
	v_readlane_b32 s0, v253, 37
	v_readlane_b32 s8, v253, 45
	v_cndmask_b32_e32 v5, v1, v5, vcc
	s_waitcnt vmcnt(0)
	v_lshlrev_b32_e32 v33, 2, v5
	v_xor_b32_e32 v5, 2, v1
	v_cmp_lt_i32_e32 vcc, v5, v3
	v_readlane_b32 s9, v253, 46
	v_readlane_b32 s10, v253, 47
	v_readlane_b32 s11, v253, 48
	v_readlane_b32 s12, v253, 49
	v_readlane_b32 s13, v253, 50
	v_readlane_b32 s14, v253, 51
	v_readlane_b32 s15, v253, 52
	v_cndmask_b32_e32 v5, v1, v5, vcc
	v_readlane_b32 s2, v253, 39
	v_readlane_b32 s8, v253, 21
	v_lshlrev_b32_e32 v120, 2, v5
	v_xor_b32_e32 v5, 4, v1
	v_readlane_b32 s3, v253, 40
	s_add_u32 s28, s2, 0xff000000
	v_mov_b32_e32 v35, 0
	v_lshlrev_b32_e32 v34, 4, v214
	v_readlane_b32 s16, v253, 29
	v_readlane_b32 s17, v253, 30
	v_cmp_lt_i32_e32 vcc, v5, v3
	v_readlane_b32 s1, v253, 38
	s_addc_u32 s29, s3, -1
	v_lshl_add_u64 v[36:37], s[16:17], 0, v[34:35]
	v_cndmask_b32_e32 v5, v1, v5, vcc
	v_lshlrev_b32_e32 v34, 3, v214
	s_add_u32 s30, s74, 0x1e00000
	v_lshlrev_b32_e32 v121, 2, v5
	v_xor_b32_e32 v5, 8, v1
	v_lshl_add_u64 v[6:7], s[74:75], 0, v[34:35]
	s_mov_b64 s[0:1], 0xc000000
	s_addc_u32 s31, s75, 0
	v_cmp_lt_i32_e32 vcc, v5, v3
	v_lshl_add_u64 v[38:39], v[6:7], 0, s[0:1]
	s_mov_b64 s[0:1], 0xd000000
	s_add_u32 s33, s74, 0x1d00000
	v_cndmask_b32_e32 v5, v1, v5, vcc
	v_lshl_add_u64 v[40:41], v[6:7], 0, s[0:1]
	s_mov_b64 s[0:1], 0xa000000
	s_addc_u32 s34, s75, 0
	v_lshlrev_b32_e32 v122, 2, v5
	v_xor_b32_e32 v5, 16, v1
	v_lshl_add_u64 v[42:43], v[6:7], 0, s[0:1]
	s_mov_b64 s[0:1], 0x2400000
	s_add_u32 s35, s74, 0x1900000
	v_cmp_lt_i32_e32 vcc, v5, v3
	v_lshl_add_u64 v[44:45], v[6:7], 0, s[0:1]
	v_readlane_b32 s0, v253, 54
	s_addc_u32 s36, s75, 0
	v_cndmask_b32_e32 v5, v1, v5, vcc
	v_readlane_b32 s1, v253, 55
	s_mov_b32 s2, s0
	s_ashr_i32 s3, s0, 31
	v_readlane_b32 s6, v253, 43
	v_lshlrev_b32_e32 v123, 2, v5
	v_xor_b32_e32 v5, 32, v1
	s_lshl_b64 s[0:1], s[2:3], 11
	v_readlane_b32 s7, v253, 44
	v_lshlrev_b32_e32 v32, 2, v214
	s_lshl_b32 s6, s96, 4
	v_cmp_lt_i32_e32 vcc, v5, v3
	v_lshl_or_b32 v46, v214, 3, s0
	v_mov_b32_e32 v47, s1
	s_lshl_b64 s[0:1], s[2:3], 12
	v_or_b32_e32 v0, 0x100, v32
	v_or_b32_e32 v2, 0x200, v32
	v_or_b32_e32 v4, 0x300, v32
	v_readlane_b32 s9, v253, 22
	v_readlane_b32 s10, v253, 23
	v_readlane_b32 s11, v253, 24
	v_readlane_b32 s12, v253, 25
	v_readlane_b32 s13, v253, 26
	v_readlane_b32 s14, v253, 27
	v_readlane_b32 s15, v253, 28
	v_cndmask_b32_e32 v1, v1, v5, vcc
	s_ashr_i32 s7, s6, 31
	v_lshl_or_b32 v48, v214, 4, s0
	s_mov_b32 s0, s2
	v_readlane_b32 s4, v253, 41
	v_readlane_b32 s5, v253, 42
	v_readlane_b32 s18, v253, 31
	v_readlane_b32 s19, v253, 32
	v_readlane_b32 s20, v253, 33
	v_readlane_b32 s21, v253, 34
	v_readlane_b32 s22, v253, 35
	v_readlane_b32 s23, v253, 36
	v_lshlrev_b32_e32 v124, 2, v1
	s_lshl_b64 s[8:9], s[2:3], 5
	s_lshl_b64 s[10:11], s[6:7], 5
	s_lshl_b64 s[12:13], s[6:7], 11
	v_mov_b32_e32 v49, s1
	s_lshl_b64 s[14:15], s[6:7], 12
	s_brev_b32 s7, 48
	s_mov_b32 s37, 0xd000000
	v_mov_b32_e32 v34, 0x1e00000
	v_mov_b32_e32 v125, 0x1d00000
	v_mov_b32_e32 v126, 0x358637bd
	s_mov_b32 s38, 0xf800000
	v_mov_b32_e32 v127, 0x260
	v_lshlrev_b32_e32 v128, 2, v0
	v_lshlrev_b32_e32 v129, 2, v2
	v_lshlrev_b32_e32 v130, 2, v4
	s_mov_b32 s39, 0xa000000
	s_mov_b32 s40, 0x2400000
	v_writelane_b32 v253, s0, 54
	s_mov_b32 s41, s2
	v_mov_b32_e32 v83, 0
	v_mov_b32_e32 v85, 0
	v_writelane_b32 v253, s1, 55
	global_load_dwordx4 v[154:157], v[36:37], off offset:1024
	global_load_dwordx4 v[158:161], v[36:37], off offset:2048
	global_load_dwordx4 v[162:165], v[36:37], off offset:3072
	s_branch .LBB0_1114

.LBB0_1116:
	s_add_i32 s4, s41, 0xfffff000
	s_lshr_b32 s4, s4, 10
	s_add_i32 s4, s4, 1
	s_and_b64 s[0:1], s[0:1], exec
	s_cselect_b32 s0, 0, s4
	s_mul_hi_u32 s1, s0, 0x6000
	s_mulk_i32 s0, 0x6000
	s_add_u32 s17, s35, s0
	s_addc_u32 s21, s36, s1
	s_add_u32 s4, s17, 0x2000
	s_addc_u32 s5, s21, 0
	s_waitcnt vmcnt(9)
	v_lshlrev_b32_e32 v112, 16, v104
	v_and_b32_e32 v113, 0xffff0000, v104
	v_lshlrev_b32_e32 v116, 16, v105
	v_and_b32_e32 v117, 0xffff0000, v105
	s_waitcnt vmcnt(5)
	v_lshlrev_b32_e32 v114, 16, v106
	v_and_b32_e32 v115, 0xffff0000, v106
	v_lshlrev_b32_e32 v118, 16, v107
	v_and_b32_e32 v119, 0xffff0000, v107
	v_lshlrev_b32_e32 v104, 16, v100
	v_and_b32_e32 v105, 0xffff0000, v100
	v_lshlrev_b32_e32 v108, 16, v101
	v_and_b32_e32 v109, 0xffff0000, v101
	s_waitcnt vmcnt(4)
	v_lshlrev_b32_e32 v106, 16, v102
	v_and_b32_e32 v107, 0xffff0000, v102
	v_lshlrev_b32_e32 v110, 16, v103
	v_and_b32_e32 v111, 0xffff0000, v103
	v_lshlrev_b32_e32 v100, 16, v98
	v_and_b32_e32 v101, 0xffff0000, v98
	v_lshlrev_b32_e32 v102, 16, v99
	v_and_b32_e32 v103, 0xffff0000, v99
	s_waitcnt vmcnt(3)
	v_lshlrev_b32_e32 v98, 16, v94
	v_and_b32_e32 v99, 0xffff0000, v94
	global_load_dwordx4 v[132:135], v91, s[4:5]
	v_lshlrev_b32_e32 v144, 16, v95
	v_and_b32_e32 v145, 0xffff0000, v95
	v_lshlrev_b32_e32 v146, 16, v92
	v_and_b32_e32 v147, 0xffff0000, v92
	v_lshlrev_b32_e32 v148, 16, v93
	v_and_b32_e32 v149, 0xffff0000, v93
	global_load_dwordx4 v[92:95], v128, s[4:5]
	global_load_dwordx4 v[136:139], v129, s[4:5]
	global_load_dwordx4 v[140:143], v130, s[4:5]
	v_fmamk_f32 v82, v96, 0x3b000000, v126
	v_mul_f32_e32 v84, 0x4f800000, v82
	v_cmp_gt_f32_e32 vcc, s38, v82
	v_fmamk_f32 v90, v90, 0x3b000000, v126
	v_mul_f32_e32 v152, 0x4f800000, v90
	v_cndmask_b32_e32 v82, v82, v84, vcc
	v_sqrt_f32_e32 v84, v82
	s_waitcnt vmcnt(6)
	v_lshlrev_b32_e32 v96, 16, v88
	v_add_u32_e32 v97, -1, v84
	v_fma_f32 v131, -v97, v84, v82
	v_cmp_ge_f32_e64 s[0:1], 0, v131
	v_add_u32_e32 v131, 1, v84
	s_nop 0
	v_cndmask_b32_e64 v97, v84, v97, s[0:1]
	v_fma_f32 v84, -v131, v84, v82
	v_cmp_lt_f32_e64 s[0:1], 0, v84
	s_nop 1
	v_cndmask_b32_e64 v84, v97, v131, s[0:1]
	v_mul_f32_e32 v97, 0x37800000, v84
	v_cndmask_b32_e32 v84, v84, v97, vcc
	v_cmp_class_f32_e32 vcc, v82, v127
	v_and_b32_e32 v97, 0xffff0000, v88
	v_lshlrev_b32_e32 v88, 16, v89
	v_cndmask_b32_e32 v82, v84, v82, vcc
	v_div_scale_f32 v84, s[0:1], v82, v82, 1.0
	v_rcp_f32_e32 v131, v84
	v_cmp_gt_f32_e64 s[0:1], s38, v90
	v_and_b32_e32 v89, 0xffff0000, v89
	v_fma_f32 v150, -v84, v131, 1.0
	v_cndmask_b32_e64 v90, v90, v152, s[0:1]
	v_fmac_f32_e32 v131, v150, v131
	v_div_scale_f32 v150, vcc, 1.0, v82, 1.0
	v_sqrt_f32_e32 v152, v90
	v_mul_f32_e32 v151, v150, v131
	v_fma_f32 v153, -v84, v151, v150
	v_fmac_f32_e32 v151, v153, v131
	v_fma_f32 v84, -v84, v151, v150
	v_add_u32_e32 v150, -1, v152
	v_fma_f32 v153, -v150, v152, v90
	v_cmp_ge_f32_e64 s[4:5], 0, v153
	v_add_u32_e32 v153, 1, v152
	v_div_fmas_f32 v84, v84, v131, v151
	v_cndmask_b32_e64 v150, v152, v150, s[4:5]
	v_fma_f32 v152, -v153, v152, v90
	v_cmp_lt_f32_e64 s[4:5], 0, v152
	v_div_fixup_f32 v82, v84, v82, 1.0
	v_pk_mul_f32 v[108:109], v[82:83], v[108:109] op_sel_hi:[0,1]
	v_cndmask_b32_e64 v150, v150, v153, s[4:5]
	v_mul_f32_e32 v152, 0x37800000, v150
	v_cndmask_b32_e64 v150, v150, v152, s[0:1]
	v_cmp_class_f32_e64 s[0:1], v90, v127
	v_pk_mul_f32 v[104:105], v[82:83], v[104:105] op_sel_hi:[0,1]
	v_pk_mul_f32 v[116:117], v[82:83], v[116:117] op_sel_hi:[0,1]
	v_cndmask_b32_e64 v90, v150, v90, s[0:1]
	v_div_scale_f32 v150, s[0:1], v90, v90, 1.0
	v_rcp_f32_e32 v152, v150
	v_pk_mul_f32 v[112:113], v[82:83], v[112:113] op_sel_hi:[0,1]
	v_pk_mul_f32 v[100:101], v[82:83], v[100:101] op_sel_hi:[0,1]
	s_add_u32 s4, s17, 0x3000
	v_fma_f32 v84, -v150, v152, 1.0
	v_fmac_f32_e32 v152, v84, v152
	v_div_scale_f32 v84, vcc, 1.0, v90, 1.0
	v_mul_f32_e32 v131, v84, v152
	v_fma_f32 v151, -v150, v131, v84
	v_fmac_f32_e32 v131, v151, v152
	v_fma_f32 v84, -v150, v131, v84
	v_div_fmas_f32 v84, v84, v152, v131
	v_div_fixup_f32 v84, v84, v90, 1.0
	v_pk_fma_f32 v[104:105], v[84:85], v[106:107], v[104:105] op_sel_hi:[0,1,1]
	v_pk_fma_f32 v[106:107], v[84:85], v[110:111], v[108:109] op_sel_hi:[0,1,1]
	s_waitcnt vmcnt(2)
	v_pk_fma_f32 v[94:95], v[94:95], v[106:107], v[22:23]
	v_pk_fma_f32 v[92:93], v[92:93], v[104:105], v[20:21]
	v_pk_mul_f32 v[20:21], v[94:95], v[94:95]
	v_pk_mul_f32 v[22:23], v[92:93], v[92:93]
	v_pk_fma_f32 v[112:113], v[84:85], v[114:115], v[112:113] op_sel_hi:[0,1,1]
	v_pk_fma_f32 v[114:115], v[84:85], v[118:119], v[116:117] op_sel_hi:[0,1,1]
	v_pk_mov_b32 v[104:105], v[22:23], v[20:21] op_sel:[1,0]
	v_mov_b32_e32 v23, v21
	v_pk_fma_f32 v[30:31], v[134:135], v[114:115], v[30:31]
	v_pk_fma_f32 v[28:29], v[132:133], v[112:113], v[28:29]
	v_pk_add_f32 v[20:21], v[104:105], v[22:23]
	v_pk_mul_f32 v[22:23], v[82:83], v[102:103] op_sel_hi:[0,1]
	v_pk_fma_f32 v[98:99], v[84:85], v[98:99], v[100:101] op_sel_hi:[0,1,1]
	v_pk_mul_f32 v[112:113], v[30:31], v[30:31]
	v_pk_mul_f32 v[114:115], v[28:29], v[28:29]
	v_pk_add_f32 v[20:21], v[20:21], v[20:21] op_sel_hi:[0,1]
	v_pk_fma_f32 v[22:23], v[84:85], v[144:145], v[22:23] op_sel_hi:[0,1,1]
	s_waitcnt vmcnt(1)
	v_pk_fma_f32 v[98:99], v[136:137], v[98:99], v[24:25]
	v_pk_mov_b32 v[116:117], v[114:115], v[112:113] op_sel:[1,0]
	v_mov_b32_e32 v115, v113
	v_pk_fma_f32 v[100:101], v[138:139], v[22:23], v[26:27]
	v_mul_f32_e32 v20, v98, v98
	v_pk_mul_f32 v[26:27], v[82:83], v[148:149] op_sel_hi:[0,1]
	v_pk_mul_f32 v[102:103], v[82:83], v[146:147] op_sel_hi:[0,1]
	v_pk_add_f32 v[112:113], v[116:117], v[114:115]
	v_pk_fma_f32 v[22:23], v[98:99], v[98:99], v[20:21] op_sel_hi:[1,1,0]
	v_mul_f32_e32 v20, v100, v100
	v_pk_fma_f32 v[96:97], v[84:85], v[96:97], v[102:103] op_sel_hi:[0,1,1]
	v_pk_fma_f32 v[26:27], v[84:85], v[88:89], v[26:27] op_sel_hi:[0,1,1]
	v_add_co_u32_e32 v106, vcc, s39, v86
	v_pk_add_f32 v[112:113], v[112:113], v[112:113] op_sel_hi:[0,1]
	v_pk_fma_f32 v[24:25], v[100:101], v[100:101], v[20:21] op_sel_hi:[1,1,0]
	s_waitcnt vmcnt(0)
	v_pk_fma_f32 v[88:89], v[142:143], v[26:27], v[18:19]
	v_pk_fma_f32 v[96:97], v[140:141], v[96:97], v[16:17]
	s_addc_u32 s5, s21, 0
	v_addc_co_u32_e32 v107, vcc, 0, v87, vcc
	v_mul_f32_e32 v22, v96, v96
	v_mul_f32_e32 v24, v97, v97
	v_mul_f32_e32 v112, v88, v88
	v_mul_f32_e32 v20, v89, v89
	s_add_u32 s20, s17, 0x4000
	v_cvt_pk_bf16_f32 v16, v28, v29
	v_cvt_pk_bf16_f32 v17, v30, v31
	global_store_dwordx2 v[106:107], v[16:17], off
	v_pk_add_f32 v[102:103], v[22:23], v[24:25]
	v_pk_add_f32 v[104:105], v[112:113], v[20:21]
	s_addc_u32 s21, s21, 0
	global_load_dwordx4 v[16:19], v[36:37], off
	global_load_dwordx4 v[20:23], v91, s[4:5]
	global_load_dwordx4 v[24:27], v91, s[20:21]
	global_load_dwordx4 v[166:169], v128, s[20:21]
	global_load_dwordx4 v[170:173], v129, s[20:21]
	global_load_dwordx4 v[174:177], v130, s[20:21]
	global_load_dwordx4 v[178:181], v128, s[4:5]
	global_load_dwordx4 v[182:185], v129, s[4:5]
	global_load_dwordx4 v[186:189], v130, s[4:5]
	v_pk_add_f32 v[102:103], v[102:103], v[104:105]
	s_waitcnt vmcnt(0)
	v_pk_add_f32 v[24:25], v[24:25], 1.0 op_sel_hi:[1,0]
	v_add_f32_e32 v82, v102, v103
	ds_bpermute_b32 v84, v33, v82
	v_pk_add_f32 v[26:27], v[26:27], 1.0 op_sel_hi:[1,0]
	s_waitcnt lgkmcnt(0)
	v_add_f32_e32 v82, v82, v84
	ds_bpermute_b32 v84, v120, v82
	s_waitcnt lgkmcnt(0)
	v_add_f32_e32 v82, v82, v84
	ds_bpermute_b32 v84, v121, v82
	s_waitcnt lgkmcnt(0)
	v_add_f32_e32 v82, v82, v84
	ds_bpermute_b32 v84, v122, v82
	s_waitcnt lgkmcnt(0)
	v_add_f32_e32 v82, v82, v84
	ds_bpermute_b32 v84, v123, v82
	s_waitcnt lgkmcnt(0)
	v_add_f32_e32 v82, v82, v84
	ds_bpermute_b32 v84, v124, v82
	s_waitcnt lgkmcnt(0)
	v_add_f32_e32 v82, v82, v84
	v_fmamk_f32 v82, v82, 0x3a800000, v126
	v_mul_f32_e32 v84, 0x4f800000, v82
	v_cmp_gt_f32_e32 vcc, s38, v82
	s_nop 1
	v_cndmask_b32_e32 v82, v82, v84, vcc
	v_sqrt_f32_e32 v84, v82
	s_nop 0
	v_add_u32_e32 v90, -1, v84
	v_fma_f32 v102, -v90, v84, v82
	v_cmp_ge_f32_e64 s[0:1], 0, v102
	v_add_u32_e32 v102, 1, v84
	s_nop 0
	v_cndmask_b32_e64 v90, v84, v90, s[0:1]
	v_fma_f32 v84, -v102, v84, v82
	v_cmp_lt_f32_e64 s[0:1], 0, v84
	s_nop 1
	v_cndmask_b32_e64 v84, v90, v102, s[0:1]
	v_mul_f32_e32 v90, 0x37800000, v84
	v_cndmask_b32_e32 v84, v84, v90, vcc
	v_cmp_class_f32_e32 vcc, v82, v127
	s_nop 1
	v_cndmask_b32_e32 v82, v84, v82, vcc
	v_div_scale_f32 v84, s[0:1], v82, v82, 1.0
	v_rcp_f32_e32 v90, v84
	s_nop 0
	v_fma_f32 v102, -v84, v90, 1.0
	v_fmac_f32_e32 v90, v102, v90
	v_div_scale_f32 v102, vcc, 1.0, v82, 1.0
	v_mul_f32_e32 v103, v102, v90
	v_fma_f32 v104, -v84, v103, v102
	v_fmac_f32_e32 v103, v104, v90
	v_fma_f32 v84, -v84, v103, v102
	v_div_fmas_f32 v84, v84, v90, v103
	v_div_fixup_f32 v82, v84, v82, 1.0
	v_pk_mul_f32 v[28:29], v[28:29], v[82:83] op_sel_hi:[1,0]
	v_pk_mul_f32 v[30:31], v[30:31], v[82:83] op_sel_hi:[1,0]
	v_pk_mul_f32 v[16:17], v[16:17], v[28:29]
	v_pk_mul_f32 v[18:19], v[18:19], v[30:31]
	v_pk_fma_f32 v[16:17], v[24:25], v[16:17], v[20:21]
	v_add_co_u32_e32 v28, vcc, s40, v86
	v_pk_fma_f32 v[18:19], v[26:27], v[18:19], v[22:23]
	v_cvt_pk_bf16_f32 v16, v16, v17
	s_nop 0
	v_addc_co_u32_e32 v29, vcc, 0, v87, vcc
	v_cvt_pk_bf16_f32 v17, v18, v19
	global_store_dwordx2 v[28:29], v[16:17], off
	v_cvt_pk_bf16_f32 v16, v92, v93
	v_cvt_pk_bf16_f32 v17, v94, v95
	global_store_dwordx2 v[106:107], v[16:17], off offset:512
	s_nop 0
	v_pk_mul_f32 v[86:87], v[92:93], v[82:83] op_sel_hi:[1,0]
	v_pk_mul_f32 v[30:31], v[94:95], v[82:83] op_sel_hi:[1,0]
	s_andn2_b64 vcc, exec, s[2:3]
	v_pk_mul_f32 v[16:17], v[154:155], v[86:87]
	v_pk_add_f32 v[20:21], v[166:167], 1.0 op_sel_hi:[1,0]
	v_pk_mul_f32 v[18:19], v[156:157], v[30:31]
	v_pk_add_f32 v[22:23], v[168:169], 1.0 op_sel_hi:[1,0]
	v_pk_fma_f32 v[16:17], v[20:21], v[16:17], v[178:179]
	v_pk_fma_f32 v[18:19], v[22:23], v[18:19], v[180:181]
	v_cvt_pk_bf16_f32 v16, v16, v17
	v_pk_mul_f32 v[86:87], v[98:99], v[82:83] op_sel_hi:[1,0]
	v_cvt_pk_bf16_f32 v17, v18, v19
	global_store_dwordx2 v[28:29], v[16:17], off offset:512
	v_cvt_pk_bf16_f32 v16, v98, v99
	v_cvt_pk_bf16_f32 v17, v100, v101
	global_store_dwordx2 v[106:107], v[16:17], off offset:1024
	s_nop 0
	v_pk_mul_f32 v[30:31], v[100:101], v[82:83] op_sel_hi:[1,0]
	v_pk_mul_f32 v[16:17], v[86:87], v[158:159]
	v_pk_add_f32 v[20:21], v[170:171], 1.0 op_sel_hi:[1,0]
	v_pk_mul_f32 v[18:19], v[30:31], v[160:161]
	v_pk_add_f32 v[22:23], v[172:173], 1.0 op_sel_hi:[1,0]
	v_pk_fma_f32 v[16:17], v[16:17], v[20:21], v[182:183]
	v_pk_fma_f32 v[18:19], v[18:19], v[22:23], v[184:185]
	v_cvt_pk_bf16_f32 v16, v16, v17
	v_pk_mul_f32 v[86:87], v[96:97], v[82:83] op_sel_hi:[1,0]
	v_cvt_pk_bf16_f32 v17, v18, v19
	global_store_dwordx2 v[28:29], v[16:17], off offset:1024
	v_cvt_pk_bf16_f32 v16, v96, v97
	v_cvt_pk_bf16_f32 v17, v88, v89
	global_store_dwordx2 v[106:107], v[16:17], off offset:1536
	s_nop 0
	v_pk_mul_f32 v[30:31], v[88:89], v[82:83] op_sel_hi:[1,0]
	v_pk_mul_f32 v[16:17], v[86:87], v[162:163]
	v_pk_add_f32 v[20:21], v[174:175], 1.0 op_sel_hi:[1,0]
	v_pk_mul_f32 v[18:19], v[30:31], v[164:165]
	v_pk_add_f32 v[22:23], v[176:177], 1.0 op_sel_hi:[1,0]
	v_pk_fma_f32 v[16:17], v[16:17], v[20:21], v[186:187]
	v_pk_fma_f32 v[18:19], v[18:19], v[22:23], v[188:189]
	v_cvt_pk_bf16_f32 v16, v16, v17
	s_nop 0
	v_cvt_pk_bf16_f32 v17, v18, v19
	global_store_dwordx2 v[28:29], v[16:17], off offset:1536
	s_cbranch_vccnz .LBB0_1113
	s_add_i32 s0, s16, 0xfffff000
	s_lshr_b32 s0, s0, 10
	s_add_i32 s0, s0, 1
	s_cmpk_gt_i32 s16, 0xfff
	s_cselect_b32 s0, s0, 0
	s_mul_hi_u32 s1, s0, 0x6000
	s_mulk_i32 s0, 0x6000
	s_add_u32 s20, s35, s0
	s_addc_u32 s21, s36, s1
	s_add_u32 s2, s20, 0x2000
	s_addc_u32 s3, s21, 0
	global_load_dwordx4 v[16:19], v91, s[2:3]
	global_load_dwordx4 v[20:23], v128, s[2:3]
	v_fmamk_f32 v24, v83, 0x3b000000, v126
	v_fmamk_f32 v25, v85, 0x3b000000, v126
	v_mul_f32_e32 v26, 0x4f800000, v24
	v_mul_f32_e32 v27, 0x4f800000, v25
	v_cmp_gt_f32_e32 vcc, s38, v24
	v_cmp_gt_f32_e64 s[0:1], s38, v25
	global_load_dwordx4 v[28:31], v130, s[2:3]
	v_cndmask_b32_e32 v82, v24, v26, vcc
	v_cndmask_b32_e64 v86, v25, v27, s[0:1]
	global_load_dwordx4 v[24:27], v129, s[2:3]
	v_sqrt_f32_e32 v84, v82
	v_sqrt_f32_e32 v87, v86
	s_ashr_i32 s17, s16, 31
	s_add_u32 s2, s20, 0x3000
	v_add_u32_e32 v88, -1, v84
	v_add_u32_e32 v90, -1, v87
	v_fma_f32 v93, -v88, v84, v82
	v_add_u32_e32 v89, 1, v84
	v_fma_f32 v95, -v90, v87, v86
	v_cmp_ge_f32_e64 s[4:5], 0, v93
	v_add_u32_e32 v92, 1, v87
	v_fma_f32 v94, -v89, v84, v82
	v_cndmask_b32_e64 v84, v84, v88, s[4:5]
	v_cmp_ge_f32_e64 s[4:5], 0, v95
	v_fma_f32 v96, -v92, v87, v86
	s_addc_u32 s3, s21, 0
	v_cndmask_b32_e64 v87, v87, v90, s[4:5]
	v_cmp_lt_f32_e64 s[4:5], 0, v94
	s_nop 1
	v_cndmask_b32_e64 v84, v84, v89, s[4:5]
	v_cmp_lt_f32_e64 s[4:5], 0, v96
	v_mul_f32_e32 v88, 0x37800000, v84
	v_cndmask_b32_e32 v84, v84, v88, vcc
	v_cndmask_b32_e64 v87, v87, v92, s[4:5]
	v_mul_f32_e32 v89, 0x37800000, v87
	v_cmp_class_f32_e32 vcc, v82, v127
	v_cndmask_b32_e64 v87, v87, v89, s[0:1]
	s_add_u32 s4, s20, 0x4000
	v_cndmask_b32_e32 v82, v84, v82, vcc
	v_cmp_class_f32_e32 vcc, v86, v127
	s_addc_u32 s5, s21, 0
	s_lshl_b64 s[16:17], s[16:17], 11
	v_cndmask_b32_e32 v84, v87, v86, vcc
	v_div_scale_f32 v86, s[0:1], v82, v82, 1.0
	v_div_scale_f32 v88, s[0:1], v84, v84, 1.0
	v_rcp_f32_e32 v89, v86
	v_rcp_f32_e32 v90, v88
	v_div_scale_f32 v87, vcc, 1.0, v82, 1.0
	v_fma_f32 v93, -v86, v89, 1.0
	v_fma_f32 v94, -v88, v90, 1.0
	v_fmac_f32_e32 v89, v93, v89
	v_div_scale_f32 v92, s[0:1], 1.0, v84, 1.0
	v_fmac_f32_e32 v90, v94, v90
	v_mul_f32_e32 v93, v87, v89
	v_mul_f32_e32 v94, v92, v90
	v_fma_f32 v95, -v86, v93, v87
	v_fma_f32 v96, -v88, v94, v92
	v_fmac_f32_e32 v93, v95, v89
	v_fmac_f32_e32 v94, v96, v90
	v_fma_f32 v86, -v86, v93, v87
	v_fma_f32 v87, -v88, v94, v92
	v_div_fmas_f32 v86, v86, v89, v93
	s_mov_b64 vcc, s[0:1]
	v_div_fixup_f32 v82, v86, v82, 1.0
	v_div_fmas_f32 v86, v87, v90, v94
	v_div_fixup_f32 v84, v86, v84, 1.0
	v_pk_mul_f32 v[86:87], v[82:83], v[62:63] op_sel_hi:[0,1]
	v_pk_mul_f32 v[88:89], v[82:83], v[50:51] op_sel_hi:[0,1]
	v_pk_fma_f32 v[88:89], v[84:85], v[58:59], v[88:89] op_sel_hi:[0,1,1]
	v_pk_fma_f32 v[86:87], v[84:85], v[70:71], v[86:87] op_sel_hi:[0,1,1]
	v_pk_mul_f32 v[92:93], v[82:83], v[68:69] op_sel_hi:[0,1]
	v_pk_mul_f32 v[94:95], v[82:83], v[52:53] op_sel_hi:[0,1]
	v_pk_fma_f32 v[94:95], v[84:85], v[60:61], v[94:95] op_sel_hi:[0,1,1]
	s_waitcnt vmcnt(3)
	v_pk_fma_f32 v[14:15], v[86:87], v[18:19], v[14:15]
	v_pk_fma_f32 v[12:13], v[88:89], v[16:17], v[12:13]
	v_pk_fma_f32 v[92:93], v[84:85], v[74:75], v[92:93] op_sel_hi:[0,1,1]
	v_pk_mul_f32 v[16:17], v[14:15], v[14:15]
	v_pk_mul_f32 v[18:19], v[12:13], v[12:13]
	s_waitcnt vmcnt(2)
	v_pk_fma_f32 v[10:11], v[92:93], v[22:23], v[10:11]
	v_pk_fma_f32 v[8:9], v[94:95], v[20:21], v[8:9]
	v_pk_mov_b32 v[20:21], v[18:19], v[16:17] op_sel:[1,0]
	v_mov_b32_e32 v19, v17
	v_pk_add_f32 v[16:17], v[20:21], v[18:19]
	v_pk_mul_f32 v[18:19], v[10:11], v[10:11]
	v_pk_mul_f32 v[20:21], v[8:9], v[8:9]
	v_pk_add_f32 v[16:17], v[16:17], v[16:17] op_sel:[0,1] op_sel_hi:[1,0]
	v_pk_mov_b32 v[22:23], v[20:21], v[18:19] op_sel:[1,0]
	v_mov_b32_e32 v21, v19
	v_pk_add_f32 v[18:19], v[22:23], v[20:21]
	v_pk_mul_f32 v[22:23], v[82:83], v[54:55] op_sel_hi:[0,1]
	v_pk_mul_f32 v[20:21], v[82:83], v[72:73] op_sel_hi:[0,1]
	v_pk_fma_f32 v[22:23], v[84:85], v[64:65], v[22:23] op_sel_hi:[0,1,1]
	v_pk_fma_f32 v[20:21], v[84:85], v[78:79], v[20:21] op_sel_hi:[0,1,1]
	s_waitcnt vmcnt(0)
	v_pk_fma_f32 v[4:5], v[22:23], v[24:25], v[4:5]
	v_pk_mul_f32 v[22:23], v[82:83], v[56:57] op_sel_hi:[0,1]
	v_pk_fma_f32 v[6:7], v[20:21], v[26:27], v[6:7]
	v_pk_mul_f32 v[20:21], v[82:83], v[76:77] op_sel_hi:[0,1]
	v_pk_fma_f32 v[22:23], v[84:85], v[66:67], v[22:23] op_sel_hi:[0,1,1]
	v_pk_fma_f32 v[20:21], v[84:85], v[80:81], v[20:21] op_sel_hi:[0,1,1]
	v_pk_fma_f32 v[0:1], v[22:23], v[28:29], v[0:1]
	v_pk_fma_f32 v[2:3], v[20:21], v[30:31], v[2:3]
	v_mul_f32_e32 v20, v0, v0
	v_mul_f32_e32 v21, v1, v1
	v_pk_add_f32 v[18:19], v[18:19], v[18:19] op_sel:[0,1] op_sel_hi:[1,0]
	v_mov_b32_e32 v17, v20
	v_mov_b32_e32 v19, v21
	v_pk_add_f32 v[28:29], v[16:17], v[18:19]
	v_mul_f32_e32 v16, v5, v5
	v_mul_f32_e32 v18, v7, v7
	v_mul_f32_e32 v22, v2, v2
	v_mul_f32_e32 v23, v3, v3
	v_pk_fma_f32 v[16:17], v[4:5], v[4:5], v[16:17] op_sel_hi:[1,1,0]
	v_pk_fma_f32 v[18:19], v[6:7], v[6:7], v[18:19] op_sel_hi:[1,1,0]
	v_mov_b32_e32 v17, v22
	v_mov_b32_e32 v19, v23
	v_lshl_add_u64 v[86:87], v[42:43], 0, s[16:17]
	v_pk_add_f32 v[30:31], v[16:17], v[18:19]
	v_cvt_pk_bf16_f32 v16, v12, v13
	v_cvt_pk_bf16_f32 v17, v14, v15
	global_store_dwordx2 v[86:87], v[16:17], off
	global_load_dwordx4 v[16:19], v[36:37], off
	s_nop 0
	global_load_dwordx4 v[20:23], v91, s[2:3]
	global_load_dwordx4 v[24:27], v91, s[4:5]
	global_load_dwordx4 v[166:169], v128, s[4:5]
	global_load_dwordx4 v[170:173], v129, s[4:5]
	global_load_dwordx4 v[174:177], v130, s[4:5]
	global_load_dwordx4 v[178:181], v128, s[2:3]
	global_load_dwordx4 v[182:185], v129, s[2:3]
	global_load_dwordx4 v[186:189], v130, s[2:3]
	v_pk_add_f32 v[28:29], v[28:29], v[30:31]
	s_waitcnt vmcnt(0)
	v_pk_add_f32 v[24:25], v[24:25], 1.0 op_sel_hi:[1,0]
	v_add_f32_e32 v28, v28, v29
	ds_bpermute_b32 v29, v33, v28
	v_pk_add_f32 v[26:27], v[26:27], 1.0 op_sel_hi:[1,0]
	s_waitcnt lgkmcnt(0)
	v_add_f32_e32 v28, v28, v29
	ds_bpermute_b32 v29, v120, v28
	s_waitcnt lgkmcnt(0)
	v_add_f32_e32 v28, v28, v29
	ds_bpermute_b32 v29, v121, v28
	s_waitcnt lgkmcnt(0)
	v_add_f32_e32 v28, v28, v29
	ds_bpermute_b32 v29, v122, v28
	s_waitcnt lgkmcnt(0)
	v_add_f32_e32 v28, v28, v29
	ds_bpermute_b32 v29, v123, v28
	s_waitcnt lgkmcnt(0)
	v_add_f32_e32 v28, v28, v29
	ds_bpermute_b32 v29, v124, v28
	s_waitcnt lgkmcnt(0)
	v_add_f32_e32 v28, v28, v29
	v_fmamk_f32 v28, v28, 0x3a800000, v126
	v_mul_f32_e32 v29, 0x4f800000, v28
	v_cmp_gt_f32_e32 vcc, s38, v28
	s_nop 1
	v_cndmask_b32_e32 v28, v28, v29, vcc
	v_sqrt_f32_e32 v29, v28
	s_nop 0
	v_add_u32_e32 v30, -1, v29
	v_fma_f32 v31, -v30, v29, v28
	v_cmp_ge_f32_e64 s[0:1], 0, v31
	v_add_u32_e32 v31, 1, v29
	s_nop 0
	v_cndmask_b32_e64 v30, v29, v30, s[0:1]
	v_fma_f32 v29, -v31, v29, v28
	v_cmp_lt_f32_e64 s[0:1], 0, v29
	s_nop 1
	v_cndmask_b32_e64 v29, v30, v31, s[0:1]
	v_mul_f32_e32 v30, 0x37800000, v29
	v_cndmask_b32_e32 v29, v29, v30, vcc
	v_cmp_class_f32_e32 vcc, v28, v127
	s_nop 1
	v_cndmask_b32_e32 v28, v29, v28, vcc
	v_div_scale_f32 v29, s[0:1], v28, v28, 1.0
	v_rcp_f32_e32 v30, v29
	s_nop 0
	v_fma_f32 v31, -v29, v30, 1.0
	v_fmac_f32_e32 v30, v31, v30
	v_div_scale_f32 v31, vcc, 1.0, v28, 1.0
	v_mul_f32_e32 v82, v31, v30
	v_fma_f32 v84, -v29, v82, v31
	v_fmac_f32_e32 v82, v84, v30
	v_fma_f32 v29, -v29, v82, v31
	v_div_fmas_f32 v29, v29, v30, v82
	v_div_fixup_f32 v28, v29, v28, 1.0
	v_pk_mul_f32 v[88:89], v[12:13], v[28:29] op_sel_hi:[1,0]
	v_pk_mul_f32 v[30:31], v[14:15], v[28:29] op_sel_hi:[1,0]
	v_pk_mul_f32 v[16:17], v[16:17], v[88:89]
	v_pk_mul_f32 v[18:19], v[18:19], v[30:31]
	v_pk_fma_f32 v[16:17], v[24:25], v[16:17], v[20:21]
	v_pk_fma_f32 v[18:19], v[26:27], v[18:19], v[22:23]
	v_cvt_pk_bf16_f32 v16, v16, v17
	v_lshl_add_u64 v[30:31], v[44:45], 0, s[16:17]
	v_cvt_pk_bf16_f32 v17, v18, v19
	global_store_dwordx2 v[30:31], v[16:17], off
	v_cvt_pk_bf16_f32 v16, v8, v9
	v_cvt_pk_bf16_f32 v17, v10, v11
	global_store_dwordx2 v[86:87], v[16:17], off offset:512
	s_nop 0
	v_pk_mul_f32 v[90:91], v[8:9], v[28:29] op_sel_hi:[1,0]
	v_pk_mul_f32 v[88:89], v[10:11], v[28:29] op_sel_hi:[1,0]
	v_pk_mul_f32 v[16:17], v[154:155], v[90:91]
	v_pk_add_f32 v[20:21], v[166:167], 1.0 op_sel_hi:[1,0]
	v_pk_mul_f32 v[18:19], v[156:157], v[88:89]
	v_pk_add_f32 v[22:23], v[168:169], 1.0 op_sel_hi:[1,0]
	v_pk_fma_f32 v[16:17], v[16:17], v[20:21], v[178:179]
	v_pk_fma_f32 v[18:19], v[18:19], v[22:23], v[180:181]
	v_cvt_pk_bf16_f32 v16, v16, v17
	v_pk_mul_f32 v[90:91], v[4:5], v[28:29] op_sel_hi:[1,0]
	v_cvt_pk_bf16_f32 v17, v18, v19
	global_store_dwordx2 v[30:31], v[16:17], off offset:512
	v_cvt_pk_bf16_f32 v16, v4, v5
	v_cvt_pk_bf16_f32 v17, v6, v7
	global_store_dwordx2 v[86:87], v[16:17], off offset:1024
	s_nop 0
	v_pk_mul_f32 v[88:89], v[6:7], v[28:29] op_sel_hi:[1,0]
	v_pk_mul_f32 v[16:17], v[90:91], v[158:159]
	v_pk_add_f32 v[20:21], v[170:171], 1.0 op_sel_hi:[1,0]
	v_pk_mul_f32 v[18:19], v[88:89], v[160:161]
	v_pk_add_f32 v[22:23], v[172:173], 1.0 op_sel_hi:[1,0]
	v_pk_fma_f32 v[16:17], v[16:17], v[20:21], v[182:183]
	v_pk_fma_f32 v[18:19], v[18:19], v[22:23], v[184:185]
	v_cvt_pk_bf16_f32 v16, v16, v17
	s_nop 0
	v_cvt_pk_bf16_f32 v17, v18, v19
	global_store_dwordx2 v[30:31], v[16:17], off offset:1024
	v_cvt_pk_bf16_f32 v16, v0, v1
	v_cvt_pk_bf16_f32 v17, v2, v3
	global_store_dwordx2 v[86:87], v[16:17], off offset:1536
	s_nop 0
	v_pk_mul_f32 v[86:87], v[2:3], v[28:29] op_sel_hi:[1,0]
	v_pk_mul_f32 v[28:29], v[0:1], v[28:29] op_sel_hi:[1,0]
	v_pk_mul_f32 v[18:19], v[86:87], v[164:165]
	v_pk_mul_f32 v[16:17], v[28:29], v[162:163]
	v_pk_add_f32 v[20:21], v[174:175], 1.0 op_sel_hi:[1,0]
	v_pk_add_f32 v[22:23], v[176:177], 1.0 op_sel_hi:[1,0]
	v_pk_fma_f32 v[16:17], v[16:17], v[20:21], v[186:187]
	v_pk_fma_f32 v[18:19], v[18:19], v[22:23], v[188:189]
	v_cvt_pk_bf16_f32 v16, v16, v17
	s_nop 0
	v_cvt_pk_bf16_f32 v17, v18, v19
	global_store_dwordx2 v[30:31], v[16:17], off offset:1536
	s_branch .LBB0_1113

.LBB0_1500:
	s_cmp_lt_i32 s94, 11
	s_cselect_b64 s[0:1], -1, 0
	s_cmp_gt_i32 s95, 10
	s_cselect_b64 s[2:3], -1, 0
	s_and_b64 s[0:1], s[0:1], s[2:3]
	s_andn2_b64 vcc, exec, s[0:1]
	s_cbranch_vccnz .LBB0_1562
	s_add_i32 s0, s50, s67
	s_add_u32 s2, s74, 0x1a00000
	s_addc_u32 s3, s75, 0
	s_ashr_i32 s51, s50, 31
	s_mul_i32 s4, s50, 0x90
	s_mul_hi_i32 s1, s50, 0x90
	s_add_u32 s6, s2, s4
	s_addc_u32 s7, s3, s1
	s_ashr_i32 s1, s0, 31
	s_mul_i32 s5, s0, 0x90
	s_mul_hi_i32 s4, s0, 0x90
	s_add_u32 s8, s2, s5
	s_addc_u32 s9, s3, s4
	s_add_u32 s12, s74, 0x2000000
	s_addc_u32 s13, s75, 0
	s_lshl_b64 s[2:3], s[50:51], 8
	s_lshl_b64 s[4:5], s[50:51], 10
	s_add_u32 s10, s12, s4
	s_addc_u32 s11, s13, s5
	s_lshl_b64 s[4:5], s[0:1], 8
	s_lshl_b64 s[0:1], s[0:1], 10
	s_add_u32 s0, s12, s0
	s_addc_u32 s1, s13, s1
	v_readlane_b32 s12, v253, 5
	s_waitcnt vmcnt(0)
	v_mov_b32_e32 v29, 0
	v_lshlrev_b32_e32 v36, 4, v214
	v_readlane_b32 s20, v253, 13
	v_readlane_b32 s21, v253, 14
	global_load_dwordx4 v[12:15], v29, s[8:9] offset:64
	global_load_dwordx4 v[20:23], v29, s[6:7] offset:64
	global_load_dwordx4 v[16:19], v29, s[8:9] offset:48
	s_nop 1
	global_load_dwordx4 v[0:3], v36, s[20:21]
	global_load_dwordx4 v[8:11], v36, s[10:11] nt
	global_load_dwordx4 v[24:27], v29, s[6:7] offset:48
	global_load_dwordx4 v[4:7], v36, s[0:1] nt
	v_lshlrev_b32_e32 v110, 2, v214
	v_readlane_b32 s13, v253, 6
	s_cmpk_lt_i32 s50, 0x2000
	v_lshlrev_b32_e32 v28, 2, v110
	v_readlane_b32 s14, v253, 7
	v_readlane_b32 s15, v253, 8
	v_readlane_b32 s16, v253, 9
	v_readlane_b32 s17, v253, 10
	v_readlane_b32 s18, v253, 11
	v_readlane_b32 s19, v253, 12
	v_readlane_b32 s22, v253, 15
	v_readlane_b32 s23, v253, 16
	v_readlane_b32 s24, v253, 17
	v_readlane_b32 s25, v253, 18
	v_readlane_b32 s26, v253, 19
	v_readlane_b32 s27, v253, 20
	s_mov_b64 s[12:13], s[20:21]
	s_cbranch_scc0 .LBB0_1508
	v_mbcnt_lo_u32_b32 v32, -1, 0
	v_mbcnt_hi_u32_b32 v32, -1, v32
	v_and_b32_e32 v33, 64, v32
	v_add_u32_e32 v33, 64, v33
	v_xor_b32_e32 v34, 1, v32
	v_cmp_lt_i32_e32 vcc, v34, v33
	s_add_u32 s6, s74, 0xa000000
	s_addc_u32 s7, s75, 0
	v_cndmask_b32_e32 v34, v32, v34, vcc
	v_lshlrev_b32_e32 v111, 2, v34
	v_xor_b32_e32 v34, 2, v32
	v_cmp_lt_i32_e32 vcc, v34, v33
	s_add_u32 s8, s74, 0x4000000
	s_addc_u32 s9, s75, 0
	v_cndmask_b32_e32 v34, v32, v34, vcc
	v_lshlrev_b32_e32 v112, 2, v34
	v_xor_b32_e32 v34, 4, v32
	v_cmp_lt_i32_e32 vcc, v34, v33
	s_add_u32 s10, s74, 0x5000000
	s_addc_u32 s11, s75, 0
	v_cndmask_b32_e32 v34, v32, v34, vcc
	v_lshlrev_b32_e32 v113, 2, v34
	v_xor_b32_e32 v34, 8, v32
	v_cmp_lt_i32_e32 vcc, v34, v33
	s_add_u32 s22, s74, 0x1900000
	s_addc_u32 s23, s75, 0
	v_cndmask_b32_e32 v34, v32, v34, vcc
	v_lshlrev_b32_e32 v114, 2, v34
	v_xor_b32_e32 v34, 16, v32
	v_cmp_lt_i32_e32 vcc, v34, v33
	s_lshl_b32 s12, s96, 4
	s_lshl_b64 s[0:1], s[50:51], 11
	v_cndmask_b32_e32 v34, v32, v34, vcc
	v_lshlrev_b32_e32 v115, 2, v34
	v_xor_b32_e32 v34, 32, v32
	v_cmp_lt_i32_e32 vcc, v34, v33
	s_add_u32 s0, s74, s0
	v_mov_b32_e32 v35, v29
	v_cndmask_b32_e32 v32, v32, v34, vcc
	v_lshlrev_b32_e32 v34, 3, v214
	s_addc_u32 s1, s75, s1
	v_lshl_add_u64 v[34:35], s[0:1], 0, v[34:35]
	s_mov_b64 s[0:1], 0xa000600
	s_ashr_i32 s13, s12, 31
	v_lshl_add_u64 v[34:35], v[34:35], 0, s[0:1]
	s_lshl_b64 s[14:15], s[12:13], 11
	s_lshl_b64 s[0:1], s[50:51], 12
	s_add_u32 s0, s72, s0
	v_mov_b32_e32 v37, v29
	s_addc_u32 s1, s73, s1
	v_or_b32_e32 v38, 0x100, v110
	v_or_b32_e32 v40, 0x200, v110
	v_or_b32_e32 v42, 0x300, v110
	v_lshl_add_u64 v[36:37], s[0:1], 0, v[36:37]
	s_mov_b64 s[0:1], 0xc00
	v_lshl_add_u64 v[30:31], s[70:71], 0, v[28:29]
	v_lshlrev_b32_e32 v116, 2, v32
	v_lshl_add_u64 v[32:33], s[72:73], 0, v[28:29]
	v_lshl_add_u64 v[36:37], v[36:37], 0, s[0:1]
	s_lshl_b64 s[16:17], s[12:13], 12
	s_mov_b32 s13, 0xfa000000
	s_mov_b32 s24, 0xfb000000
	v_lshlrev_b32_e32 v29, 2, v38
	v_lshlrev_b32_e32 v117, 2, v40
	v_lshlrev_b32_e32 v118, 2, v42
	v_mov_b32_e32 v119, 0x358637bd
	s_mov_b32 s25, 0xf800000
	v_mov_b32_e32 v120, 0x260
	global_load_dwordx4 v[166:169], v[30:31], off offset:1024
	global_load_dwordx4 v[170:173], v[30:31], off offset:2048
	global_load_dwordx4 v[174:177], v[30:31], off offset:3072
	s_branch .LBB0_1504

.LBB0_1506:
	s_add_i32 s0, s50, 0xfffff000
	s_lshr_b32 s0, s0, 10
	s_add_i32 s0, s0, 1
	s_cmpk_gt_i32 s50, 0xfff
	s_cselect_b32 s0, s0, 0
	s_mul_hi_u32 s1, s0, 0x6000
	s_mulk_i32 s0, 0x6000
	s_add_u32 s0, s22, s0
	s_addc_u32 s1, s23, s1
	s_add_u32 s0, s0, 0x5000
	s_addc_u32 s1, s1, 0
	global_load_dwordx4 v[122:125], v28, s[0:1]
	global_load_dwordx4 v[126:129], v29, s[0:1]
	global_load_dwordx4 v[130:133], v117, s[0:1]
	global_load_dwordx4 v[134:137], v118, s[0:1]
	s_waitcnt vmcnt(11)
	v_lshlrev_b32_e32 v140, 16, v106
	v_and_b32_e32 v141, 0xffff0000, v106
	v_lshlrev_b32_e32 v106, 16, v107
	v_and_b32_e32 v107, 0xffff0000, v107
	s_waitcnt vmcnt(7)
	v_lshlrev_b32_e32 v142, 16, v108
	v_and_b32_e32 v143, 0xffff0000, v108
	v_lshlrev_b32_e32 v108, 16, v109
	v_and_b32_e32 v109, 0xffff0000, v109
	v_lshlrev_b32_e32 v146, 16, v100
	v_and_b32_e32 v147, 0xffff0000, v100
	v_lshlrev_b32_e32 v100, 16, v101
	v_and_b32_e32 v101, 0xffff0000, v101
	s_waitcnt vmcnt(6)
	v_lshlrev_b32_e32 v148, 16, v102
	v_and_b32_e32 v149, 0xffff0000, v102
	v_lshlrev_b32_e32 v102, 16, v103
	v_and_b32_e32 v103, 0xffff0000, v103
	v_lshlrev_b32_e32 v138, 16, v104
	v_and_b32_e32 v139, 0xffff0000, v104
	v_lshlrev_b32_e32 v104, 16, v105
	v_and_b32_e32 v105, 0xffff0000, v105
	v_lshlrev_b32_e32 v144, 16, v98
	v_and_b32_e32 v145, 0xffff0000, v98
	v_lshlrev_b32_e32 v98, 16, v99
	v_and_b32_e32 v99, 0xffff0000, v99
	v_lshlrev_b32_e32 v152, 16, v94
	v_and_b32_e32 v153, 0xffff0000, v94
	v_lshlrev_b32_e32 v94, 16, v95
	v_and_b32_e32 v95, 0xffff0000, v95
	s_waitcnt vmcnt(5)
	v_lshlrev_b32_e32 v154, 16, v96
	v_and_b32_e32 v155, 0xffff0000, v96
	v_lshlrev_b32_e32 v96, 16, v97
	v_and_b32_e32 v97, 0xffff0000, v97
	v_lshlrev_b32_e32 v158, 16, v88
	v_and_b32_e32 v159, 0xffff0000, v88
	v_lshlrev_b32_e32 v88, 16, v89
	v_and_b32_e32 v89, 0xffff0000, v89
	s_waitcnt vmcnt(4)
	v_lshlrev_b32_e32 v160, 16, v90
	v_and_b32_e32 v161, 0xffff0000, v90
	v_lshlrev_b32_e32 v90, 16, v91
	v_and_b32_e32 v91, 0xffff0000, v91
	v_pk_add_f32 v[140:141], v[140:141], v[142:143]
	v_pk_add_f32 v[106:107], v[106:107], v[108:109]
	v_pk_add_f32 v[108:109], v[146:147], v[148:149]
	v_pk_add_f32 v[100:101], v[100:101], v[102:103]
	v_lshlrev_b32_e32 v150, 16, v92
	v_and_b32_e32 v151, 0xffff0000, v92
	v_lshlrev_b32_e32 v92, 16, v93
	v_and_b32_e32 v93, 0xffff0000, v93
	v_lshlrev_b32_e32 v156, 16, v86
	v_and_b32_e32 v157, 0xffff0000, v86
	v_lshlrev_b32_e32 v86, 16, v87
	v_and_b32_e32 v87, 0xffff0000, v87
	v_pk_add_f32 v[102:103], v[152:153], v[154:155]
	v_pk_add_f32 v[94:95], v[94:95], v[96:97]
	v_pk_add_f32 v[88:89], v[88:89], v[90:91]
	v_pk_add_f32 v[96:97], v[158:159], v[160:161]
	s_waitcnt vmcnt(3)
	v_pk_fma_f32 v[90:91], v[106:107], v[124:125], v[104:105]
	v_pk_fma_f32 v[104:105], v[140:141], v[122:123], v[138:139]
	s_waitcnt vmcnt(2)
	v_pk_fma_f32 v[98:99], v[100:101], v[128:129], v[98:99]
	v_pk_fma_f32 v[100:101], v[108:109], v[126:127], v[144:145]
	s_waitcnt vmcnt(1)
	v_pk_fma_f32 v[92:93], v[94:95], v[132:133], v[92:93]
	v_pk_fma_f32 v[94:95], v[102:103], v[130:131], v[150:151]
	s_waitcnt vmcnt(0)
	v_pk_fma_f32 v[102:103], v[88:89], v[136:137], v[86:87]
	v_pk_mul_f32 v[86:87], v[104:105], v[104:105]
	v_pk_mul_f32 v[88:89], v[90:91], v[90:91]
	v_pk_mul_f32 v[106:107], v[100:101], v[100:101]
	v_pk_mul_f32 v[108:109], v[98:99], v[98:99]
	v_pk_mov_b32 v[122:123], v[86:87], v[88:89] op_sel:[1,0]
	v_mov_b32_e32 v87, v89
	v_pk_mov_b32 v[88:89], v[106:107], v[108:109] op_sel:[1,0]
	v_mov_b32_e32 v107, v109
	v_pk_fma_f32 v[96:97], v[96:97], v[134:135], v[156:157]
	v_pk_add_f32 v[86:87], v[122:123], v[86:87]
	v_pk_add_f32 v[88:89], v[88:89], v[106:107]
	v_mul_f32_e32 v121, v96, v96
	v_mul_f32_e32 v124, v97, v97
	v_pk_add_f32 v[86:87], v[86:87], v[86:87] op_sel:[0,1] op_sel_hi:[1,0]
	v_pk_add_f32 v[88:89], v[88:89], v[88:89] op_sel:[0,1] op_sel_hi:[1,0]
	v_mov_b32_e32 v87, v121
	v_mov_b32_e32 v89, v124
	v_pk_add_f32 v[106:107], v[86:87], v[88:89]
	v_mul_f32_e32 v86, v95, v95
	v_pk_fma_f32 v[108:109], v[94:95], v[94:95], v[86:87] op_sel_hi:[1,1,0]
	global_load_dwordx4 v[86:89], v[30:31], off
	v_mul_f32_e32 v122, v93, v93
	v_mul_f32_e32 v125, v102, v102
	v_mul_f32_e32 v126, v103, v103
	v_pk_fma_f32 v[122:123], v[92:93], v[92:93], v[122:123] op_sel_hi:[1,1,0]
	v_mov_b32_e32 v109, v125
	v_mov_b32_e32 v123, v126
	v_pk_add_f32 v[108:109], v[108:109], v[122:123]
	s_nop 0
	v_pk_add_f32 v[106:107], v[106:107], v[108:109]
	s_nop 0
	v_add_f32_e32 v106, v106, v107
	ds_bpermute_b32 v107, v111, v106
	s_waitcnt lgkmcnt(0)
	v_add_f32_e32 v106, v106, v107
	ds_bpermute_b32 v107, v112, v106
	s_waitcnt lgkmcnt(0)
	v_add_f32_e32 v106, v106, v107
	ds_bpermute_b32 v107, v113, v106
	s_waitcnt lgkmcnt(0)
	v_add_f32_e32 v106, v106, v107
	ds_bpermute_b32 v107, v114, v106
	s_waitcnt lgkmcnt(0)
	v_add_f32_e32 v106, v106, v107
	ds_bpermute_b32 v107, v115, v106
	s_waitcnt lgkmcnt(0)
	v_add_f32_e32 v106, v106, v107
	ds_bpermute_b32 v107, v116, v106
	s_waitcnt lgkmcnt(0)
	v_add_f32_e32 v106, v106, v107
	v_fmamk_f32 v106, v106, 0x3a800000, v119
	v_mul_f32_e32 v107, 0x4f800000, v106
	v_cmp_gt_f32_e32 vcc, s25, v106
	s_nop 1
	v_cndmask_b32_e32 v106, v106, v107, vcc
	v_sqrt_f32_e32 v107, v106
	s_nop 0
	v_add_u32_e32 v108, -1, v107
	v_add_u32_e32 v109, 1, v107
	v_fma_f32 v121, -v108, v107, v106
	v_fma_f32 v122, -v109, v107, v106
	v_cmp_ge_f32_e64 s[0:1], 0, v121
	s_nop 1
	v_cndmask_b32_e64 v107, v107, v108, s[0:1]
	v_cmp_lt_f32_e64 s[0:1], 0, v122
	s_nop 1
	v_cndmask_b32_e64 v107, v107, v109, s[0:1]
	v_mul_f32_e32 v108, 0x37800000, v107
	v_cndmask_b32_e32 v107, v107, v108, vcc
	v_cmp_class_f32_e32 vcc, v106, v120
	s_nop 1
	v_cndmask_b32_e32 v106, v107, v106, vcc
	v_div_scale_f32 v107, s[0:1], v106, v106, 1.0
	v_rcp_f32_e32 v108, v107
	v_div_scale_f32 v109, vcc, 1.0, v106, 1.0
	v_fma_f32 v121, -v107, v108, 1.0
	v_fmac_f32_e32 v108, v121, v108
	v_mul_f32_e32 v121, v109, v108
	v_fma_f32 v122, -v107, v121, v109
	v_fmac_f32_e32 v121, v122, v108
	v_fma_f32 v107, -v107, v121, v109
	v_div_fmas_f32 v107, v107, v108, v121
	v_div_fixup_f32 v106, v107, v106, 1.0
	v_pk_mul_f32 v[104:105], v[104:105], v[106:107] op_sel_hi:[1,0]
	v_pk_mul_f32 v[90:91], v[90:91], v[106:107] op_sel_hi:[1,0]
	s_waitcnt vmcnt(0)
	v_pk_mul_f32 v[86:87], v[86:87], v[104:105]
	v_pk_mul_f32 v[88:89], v[88:89], v[90:91]
	global_store_dwordx4 v[36:37], v[86:89], off offset:-3072 nt
	v_pk_mul_f32 v[90:91], v[98:99], v[106:107] op_sel_hi:[1,0]
	v_pk_mul_f32 v[98:99], v[100:101], v[106:107] op_sel_hi:[1,0]
	s_andn2_b64 vcc, exec, s[20:21]
	v_pk_mul_f32 v[86:87], v[166:167], v[98:99]
	v_pk_mul_f32 v[88:89], v[168:169], v[90:91]
	global_store_dwordx4 v[36:37], v[86:89], off offset:-2048 nt
	v_pk_mul_f32 v[90:91], v[92:93], v[106:107] op_sel_hi:[1,0]
	v_pk_mul_f32 v[92:93], v[94:95], v[106:107] op_sel_hi:[1,0]
	v_pk_mul_f32 v[88:89], v[172:173], v[90:91]
	v_pk_mul_f32 v[86:87], v[170:171], v[92:93]
	global_store_dwordx4 v[36:37], v[86:89], off offset:-1024 nt
	v_pk_mul_f32 v[90:91], v[102:103], v[106:107] op_sel_hi:[1,0]
	v_pk_mul_f32 v[92:93], v[96:97], v[106:107] op_sel_hi:[1,0]
	v_pk_mul_f32 v[88:89], v[176:177], v[90:91]
	v_pk_mul_f32 v[86:87], v[174:175], v[92:93]
	global_store_dwordx4 v[36:37], v[86:89], off nt
	s_cbranch_vccnz .LBB0_1503
	s_add_i32 s0, s18, 0xfffff000
	s_lshr_b32 s0, s0, 10
	s_add_i32 s0, s0, 1
	s_cmpk_gt_i32 s18, 0xfff
	s_cselect_b32 s0, s0, 0
	s_mul_hi_u32 s1, s0, 0x6000
	s_mulk_i32 s0, 0x6000
	s_add_u32 s0, s22, s0
	s_addc_u32 s1, s23, s1
	s_add_u32 s0, s0, 0x5000
	s_addc_u32 s1, s1, 0
	global_load_dwordx4 v[86:89], v28, s[0:1]
	global_load_dwordx4 v[90:93], v29, s[0:1]
	global_load_dwordx4 v[94:97], v117, s[0:1]
	global_load_dwordx4 v[98:101], v118, s[0:1]
	global_load_dwordx4 v[102:105], v[30:31], off
	v_pk_add_f32 v[106:107], v[58:59], v[64:65]
	v_pk_add_f32 v[108:109], v[44:45], v[54:55]
	v_pk_add_f32 v[122:123], v[68:69], v[74:75]
	v_pk_add_f32 v[124:125], v[48:49], v[60:61]
	v_pk_add_f32 v[126:127], v[76:77], v[80:81]
	v_pk_add_f32 v[128:129], v[50:51], v[66:67]
	v_pk_add_f32 v[132:133], v[56:57], v[72:73]
	v_pk_add_f32 v[130:131], v[82:83], v[84:85]
	s_ashr_i32 s19, s18, 31
	s_lshl_b64 s[18:19], s[18:19], 12
	s_waitcnt vmcnt(4)
	v_pk_fma_f32 v[52:53], v[106:107], v[88:89], v[52:53]
	v_pk_fma_f32 v[38:39], v[108:109], v[86:87], v[38:39]
	s_waitcnt vmcnt(3)
	v_pk_fma_f32 v[62:63], v[122:123], v[92:93], v[62:63]
	v_pk_fma_f32 v[40:41], v[124:125], v[90:91], v[40:41]
	v_pk_mul_f32 v[86:87], v[52:53], v[52:53]
	v_pk_mul_f32 v[88:89], v[38:39], v[38:39]
	v_pk_mul_f32 v[90:91], v[62:63], v[62:63]
	v_pk_mul_f32 v[92:93], v[40:41], v[40:41]
	s_waitcnt vmcnt(2)
	v_pk_fma_f32 v[70:71], v[126:127], v[96:97], v[70:71]
	v_pk_fma_f32 v[42:43], v[128:129], v[94:95], v[42:43]
	s_waitcnt vmcnt(1)
	v_pk_fma_f32 v[46:47], v[132:133], v[98:99], v[46:47]
	v_pk_mov_b32 v[98:99], v[88:89], v[86:87] op_sel:[1,0]
	v_mov_b32_e32 v89, v87
	v_pk_mov_b32 v[86:87], v[92:93], v[90:91] op_sel:[1,0]
	v_mov_b32_e32 v93, v91
	v_pk_fma_f32 v[78:79], v[130:131], v[100:101], v[78:79]
	v_mul_f32_e32 v97, v46, v46
	v_mul_f32_e32 v94, v43, v43
	v_mul_f32_e32 v96, v71, v71
	v_pk_add_f32 v[88:89], v[98:99], v[88:89]
	v_pk_add_f32 v[86:87], v[86:87], v[92:93]
	v_mul_f32_e32 v100, v47, v47
	v_mul_f32_e32 v101, v78, v78
	v_mul_f32_e32 v106, v79, v79
	v_pk_fma_f32 v[90:91], v[42:43], v[42:43], v[94:95] op_sel_hi:[1,1,0]
	v_pk_fma_f32 v[94:95], v[70:71], v[70:71], v[96:97] op_sel_hi:[1,1,0]
	v_pk_add_f32 v[88:89], v[88:89], v[88:89] op_sel:[0,1] op_sel_hi:[1,0]
	v_pk_add_f32 v[86:87], v[86:87], v[86:87] op_sel:[0,1] op_sel_hi:[1,0]
	v_mov_b32_e32 v91, v101
	v_mov_b32_e32 v95, v106
	v_mov_b32_e32 v89, v97
	v_mov_b32_e32 v87, v100
	v_pk_add_f32 v[90:91], v[90:91], v[94:95]
	v_pk_add_f32 v[86:87], v[88:89], v[86:87]
	s_nop 0
	v_pk_add_f32 v[86:87], v[86:87], v[90:91]
	s_nop 0
	v_add_f32_e32 v86, v86, v87
	ds_bpermute_b32 v87, v111, v86
	s_waitcnt lgkmcnt(0)
	v_add_f32_e32 v86, v86, v87
	ds_bpermute_b32 v87, v112, v86
	s_waitcnt lgkmcnt(0)
	v_add_f32_e32 v86, v86, v87
	ds_bpermute_b32 v87, v113, v86
	s_waitcnt lgkmcnt(0)
	v_add_f32_e32 v86, v86, v87
	ds_bpermute_b32 v87, v114, v86
	s_waitcnt lgkmcnt(0)
	v_add_f32_e32 v86, v86, v87
	ds_bpermute_b32 v87, v115, v86
	s_waitcnt lgkmcnt(0)
	v_add_f32_e32 v86, v86, v87
	ds_bpermute_b32 v87, v116, v86
	s_waitcnt lgkmcnt(0)
	v_add_f32_e32 v86, v86, v87
	v_fmamk_f32 v86, v86, 0x3a800000, v119
	v_mul_f32_e32 v87, 0x4f800000, v86
	v_cmp_gt_f32_e32 vcc, s25, v86
	s_nop 1
	v_cndmask_b32_e32 v86, v86, v87, vcc
	v_sqrt_f32_e32 v87, v86
	s_nop 0
	v_add_u32_e32 v88, -1, v87
	v_add_u32_e32 v89, 1, v87
	v_fma_f32 v90, -v88, v87, v86
	v_fma_f32 v91, -v89, v87, v86
	v_cmp_ge_f32_e64 s[0:1], 0, v90
	s_nop 1
	v_cndmask_b32_e64 v87, v87, v88, s[0:1]
	v_cmp_lt_f32_e64 s[0:1], 0, v91
	v_lshl_add_u64 v[90:91], v[32:33], 0, s[18:19]
	s_nop 0
	v_cndmask_b32_e64 v87, v87, v89, s[0:1]
	v_mul_f32_e32 v88, 0x37800000, v87
	v_cndmask_b32_e32 v87, v87, v88, vcc
	v_cmp_class_f32_e32 vcc, v86, v120
	s_nop 1
	v_cndmask_b32_e32 v86, v87, v86, vcc
	v_div_scale_f32 v87, s[0:1], v86, v86, 1.0
	v_rcp_f32_e32 v88, v87
	v_div_scale_f32 v89, vcc, 1.0, v86, 1.0
	v_fma_f32 v92, -v87, v88, 1.0
	v_fmac_f32_e32 v88, v92, v88
	v_mul_f32_e32 v92, v89, v88
	v_fma_f32 v93, -v87, v92, v89
	v_fmac_f32_e32 v92, v93, v88
	v_fma_f32 v87, -v87, v92, v89
	v_div_fmas_f32 v87, v87, v88, v92
	v_div_fixup_f32 v92, v87, v86, 1.0
	v_pk_mul_f32 v[86:87], v[38:39], v[92:93] op_sel_hi:[1,0]
	v_pk_mul_f32 v[88:89], v[52:53], v[92:93] op_sel_hi:[1,0]
	s_waitcnt vmcnt(0)
	v_pk_mul_f32 v[86:87], v[102:103], v[86:87]
	v_pk_mul_f32 v[88:89], v[104:105], v[88:89]
	global_store_dwordx4 v[90:91], v[86:89], off nt
	v_pk_mul_f32 v[94:95], v[62:63], v[92:93] op_sel_hi:[1,0]
	v_pk_mul_f32 v[96:97], v[40:41], v[92:93] op_sel_hi:[1,0]
	v_pk_mul_f32 v[88:89], v[168:169], v[94:95]
	v_pk_mul_f32 v[86:87], v[166:167], v[96:97]
	global_store_dwordx4 v[90:91], v[86:89], off offset:1024 nt
	v_pk_mul_f32 v[94:95], v[70:71], v[92:93] op_sel_hi:[1,0]
	v_pk_mul_f32 v[96:97], v[42:43], v[92:93] op_sel_hi:[1,0]
	v_pk_mul_f32 v[88:89], v[172:173], v[94:95]
	v_pk_mul_f32 v[86:87], v[170:171], v[96:97]
	global_store_dwordx4 v[90:91], v[86:89], off offset:2048 nt
	v_pk_mul_f32 v[94:95], v[78:79], v[92:93] op_sel_hi:[1,0]
	v_pk_mul_f32 v[92:93], v[46:47], v[92:93] op_sel_hi:[1,0]
	v_pk_mul_f32 v[88:89], v[176:177], v[94:95]
	v_pk_mul_f32 v[86:87], v[174:175], v[92:93]
	global_store_dwordx4 v[90:91], v[86:89], off offset:3072 nt
	s_branch .LBB0_1503
